# attention items (latent + context): the epilogue's 12 gate/sub-LN-weight loads issued together after the barrier instead of 8 serialized load->vmcnt(0) round trips that also waited on store acks
# speedup vs baseline: 1.0157x; 1.0043x over previous
.LBB0_702:
	s_waitcnt vmcnt(7)
	v_xor_b32_e32 v0, 1, v151
	v_cmp_lt_i32_e32 vcc, v0, v187
	v_add_f32_e32 v2, v205, v206
	s_mov_b32 s22, 0x3fb8aa3b
	v_cndmask_b32_e32 v0, v151, v0, vcc
	v_lshlrev_b32_e32 v0, 2, v0
	ds_bpermute_b32 v3, v0, v2
	v_add_f32_e32 v1, v207, v208
	ds_bpermute_b32 v0, v0, v1
	s_mov_b32 s23, 0xc2ce8ed0
	s_mov_b32 s36, 0x42b17218
	s_waitcnt lgkmcnt(1)
	v_add_f32_e32 v2, v2, v3
	v_mul_f32_e32 v3, 0x3fb8aa3b, v2
	s_waitcnt vmcnt(6)
	v_fma_f32 v4, v2, s22, -v3
	v_rndne_f32_e32 v5, v3
	v_fmac_f32_e32 v4, 0x32a5705f, v2
	v_sub_f32_e32 v3, v3, v5
	v_add_f32_e32 v3, v3, v4
	v_exp_f32_e32 v3, v3
	v_cvt_i32_f32_e32 v4, v5
	v_cmp_ngt_f32_e32 vcc, s23, v2
	s_waitcnt lgkmcnt(0)
	v_add_f32_e32 v0, v1, v0
	v_mul_f32_e32 v1, 0x3fb8aa3b, v0
	v_ldexp_f32 v3, v3, v4
	v_cndmask_b32_e32 v3, 0, v3, vcc
	v_cmp_nlt_f32_e32 vcc, s36, v2
	v_rndne_f32_e32 v4, v1
	s_movk_i32 s52, 0x210
	v_cndmask_b32_e32 v2, v200, v3, vcc
	v_fma_f32 v3, v0, s22, -v1
	v_fmac_f32_e32 v3, 0x32a5705f, v0
	v_sub_f32_e32 v1, v1, v4
	v_add_f32_e32 v1, v1, v3
	v_exp_f32_e32 v1, v1
	v_cvt_i32_f32_e32 v3, v4
	v_cmp_ngt_f32_e32 vcc, s23, v0
	s_barrier
	v_ldexp_f32 v1, v1, v3
	v_cndmask_b32_e32 v1, 0, v1, vcc
	v_cmp_nlt_f32_e32 vcc, s36, v0
	s_lshl_b32 s70, s21, 1
	s_nop 0
	v_cndmask_b32_e32 v0, v200, v1, vcc
	ds_bpermute_b32 v1, v182, v133
	v_sub_f32_e32 v0, v2, v0
	v_readlane_b32 s36, v253, 12
	v_readlane_b32 s48, v253, 24
	v_readlane_b32 s49, v253, 25
	s_waitcnt lgkmcnt(0)
	v_add_f32_e32 v1, v133, v1
	ds_bpermute_b32 v2, v181, v1
	s_mov_b32 s21, 0xcc00000
	v_readlane_b32 s37, v253, 13
	v_readlane_b32 s38, v253, 14
	v_readlane_b32 s39, v253, 15
	s_waitcnt lgkmcnt(0)
	v_add_f32_e32 v2, v1, v2
	ds_bpermute_b32 v1, v182, v132
	v_div_scale_f32 v3, s[22:23], v2, v2, 1.0
	v_rcp_f32_e32 v4, v3
	v_readlane_b32 s40, v253, 16
	s_waitcnt lgkmcnt(0)
	v_add_f32_e32 v1, v132, v1
	ds_bpermute_b32 v151, v181, v1
	v_fma_f32 v5, -v3, v4, 1.0
	v_fmac_f32_e32 v4, v5, v4
	v_div_scale_f32 v5, vcc, 1.0, v2, 1.0
	v_mul_f32_e32 v6, v5, v4
	v_fma_f32 v7, -v3, v6, v5
	v_fmac_f32_e32 v6, v7, v4
	v_fma_f32 v3, -v3, v6, v5
	s_waitcnt lgkmcnt(0)
	v_pk_add_f32 v[0:1], v[150:151], v[0:1]
	v_div_fmas_f32 v3, v3, v4, v6
	v_div_fixup_f32 v2, v3, v2, 1.0
	v_div_scale_f32 v3, s[22:23], v1, v1, v0
	v_rcp_f32_e32 v4, v3
	v_readlane_b32 s22, v251, 41
	v_readlane_b32 s41, v253, 17
	v_readlane_b32 s42, v253, 18
	v_fma_f32 v5, -v3, v4, 1.0
	v_fmac_f32_e32 v4, v5, v4
	v_div_scale_f32 v5, vcc, v0, v1, v0
	v_mul_f32_e32 v6, v5, v4
	v_fma_f32 v7, -v3, v6, v5
	v_fmac_f32_e32 v6, v7, v4
	v_fma_f32 v3, -v3, v6, v5
	v_div_fmas_f32 v3, v3, v4, v6
	v_div_fixup_f32 v0, v3, v1, v0
	v_or_b32_e32 v1, v184, v183
	v_mul_lo_u32 v1, v1, s52
	v_lshlrev_b32_e32 v3, 2, v204
	v_pk_mul_f32 v[4:5], v[76:77], v[0:1] op_sel_hi:[1,0]
	s_waitcnt vmcnt(5)
	v_pk_mul_f32 v[8:9], v[78:79], v[0:1] op_sel_hi:[1,0]
	v_pk_fma_f32 v[4:5], v[108:109], v[2:3], v[4:5] op_sel_hi:[1,0,1] neg_lo:[0,0,1] neg_hi:[0,0,1]
	v_add3_u32 v112, s17, v1, v3
	v_pk_mul_f32 v[6:7], v[4:5], v[4:5]
	v_pk_fma_f32 v[8:9], v[110:111], v[2:3], v[8:9] op_sel_hi:[1,0,1] neg_lo:[0,0,1] neg_hi:[0,0,1]
	s_waitcnt vmcnt(4)
	v_pk_mul_f32 v[12:13], v[68:69], v[0:1] op_sel_hi:[1,0]
	v_pk_mul_f32 v[16:17], v[70:71], v[0:1] op_sel_hi:[1,0]
	s_waitcnt vmcnt(3)
	v_pk_mul_f32 v[20:21], v[52:53], v[0:1] op_sel_hi:[1,0]
	v_pk_mul_f32 v[24:25], v[54:55], v[0:1] op_sel_hi:[1,0]
	s_waitcnt vmcnt(2)
	v_pk_mul_f32 v[28:29], v[48:49], v[0:1] op_sel_hi:[1,0]
	v_pk_mul_f32 v[32:33], v[50:51], v[0:1] op_sel_hi:[1,0]
	v_pk_mul_f32 v[36:37], v[72:73], v[0:1] op_sel_hi:[1,0]
	s_waitcnt vmcnt(1)
	v_pk_mul_f32 v[40:41], v[74:75], v[0:1] op_sel_hi:[1,0]
	s_waitcnt vmcnt(0)
	v_pk_mul_f32 v[44:45], v[64:65], v[0:1] op_sel_hi:[1,0]
	v_pk_mul_f32 v[48:49], v[66:67], v[0:1] op_sel_hi:[1,0]
	v_pk_mul_f32 v[52:53], v[60:61], v[0:1] op_sel_hi:[1,0]
	v_pk_mul_f32 v[60:61], v[62:63], v[0:1] op_sel_hi:[1,0]
	v_pk_mul_f32 v[56:57], v[56:57], v[0:1] op_sel_hi:[1,0]
	v_pk_mul_f32 v[0:1], v[58:59], v[0:1] op_sel_hi:[1,0]
	v_pk_mul_f32 v[10:11], v[8:9], v[8:9]
	v_pk_fma_f32 v[12:13], v[104:105], v[2:3], v[12:13] op_sel_hi:[1,0,1] neg_lo:[0,0,1] neg_hi:[0,0,1]
	v_pk_fma_f32 v[16:17], v[106:107], v[2:3], v[16:17] op_sel_hi:[1,0,1] neg_lo:[0,0,1] neg_hi:[0,0,1]
	v_pk_fma_f32 v[20:21], v[100:101], v[2:3], v[20:21] op_sel_hi:[1,0,1] neg_lo:[0,0,1] neg_hi:[0,0,1]
	v_pk_fma_f32 v[24:25], v[102:103], v[2:3], v[24:25] op_sel_hi:[1,0,1] neg_lo:[0,0,1] neg_hi:[0,0,1]
	v_pk_fma_f32 v[28:29], v[92:93], v[2:3], v[28:29] op_sel_hi:[1,0,1] neg_lo:[0,0,1] neg_hi:[0,0,1]
	v_pk_fma_f32 v[32:33], v[94:95], v[2:3], v[32:33] op_sel_hi:[1,0,1] neg_lo:[0,0,1] neg_hi:[0,0,1]
	v_pk_fma_f32 v[36:37], v[96:97], v[2:3], v[36:37] op_sel_hi:[1,0,1] neg_lo:[0,0,1] neg_hi:[0,0,1]
	v_pk_fma_f32 v[40:41], v[98:99], v[2:3], v[40:41] op_sel_hi:[1,0,1] neg_lo:[0,0,1] neg_hi:[0,0,1]
	v_pk_fma_f32 v[44:45], v[88:89], v[2:3], v[44:45] op_sel_hi:[1,0,1] neg_lo:[0,0,1] neg_hi:[0,0,1]
	v_pk_fma_f32 v[48:49], v[90:91], v[2:3], v[48:49] op_sel_hi:[1,0,1] neg_lo:[0,0,1] neg_hi:[0,0,1]
	v_pk_fma_f32 v[52:53], v[84:85], v[2:3], v[52:53] op_sel_hi:[1,0,1] neg_lo:[0,0,1] neg_hi:[0,0,1]
	v_pk_fma_f32 v[60:61], v[86:87], v[2:3], v[60:61] op_sel_hi:[1,0,1] neg_lo:[0,0,1] neg_hi:[0,0,1]
	v_pk_fma_f32 v[56:57], v[80:81], v[2:3], v[56:57] op_sel_hi:[1,0,1] neg_lo:[0,0,1] neg_hi:[0,0,1]
	v_pk_fma_f32 v[58:59], v[82:83], v[2:3], v[0:1] op_sel_hi:[1,0,1] neg_lo:[0,0,1] neg_hi:[0,0,1]
	v_add_f32_e32 v2, v6, v7
	v_add_f32_e32 v2, v10, v2
	v_pk_mul_f32 v[14:15], v[12:13], v[12:13]
	v_add_f32_e32 v2, v11, v2
	v_add_f32_e32 v2, v14, v2
	v_pk_mul_f32 v[18:19], v[16:17], v[16:17]
	v_add_f32_e32 v2, v15, v2
	v_add_f32_e32 v2, v18, v2
	v_pk_mul_f32 v[22:23], v[20:21], v[20:21]
	v_add_f32_e32 v2, v19, v2
	v_add_f32_e32 v2, v22, v2
	v_pk_mul_f32 v[26:27], v[24:25], v[24:25]
	v_add_f32_e32 v2, v23, v2
	v_add_f32_e32 v2, v26, v2
	v_pk_mul_f32 v[30:31], v[28:29], v[28:29]
	v_add_f32_e32 v2, v27, v2
	v_add_f32_e32 v2, v30, v2
	v_pk_mul_f32 v[34:35], v[32:33], v[32:33]
	v_add_f32_e32 v2, v31, v2
	v_add_f32_e32 v2, v34, v2
	v_pk_mul_f32 v[38:39], v[36:37], v[36:37]
	v_add_f32_e32 v2, v35, v2
	v_add_f32_e32 v2, v38, v2
	v_pk_mul_f32 v[42:43], v[40:41], v[40:41]
	v_add_f32_e32 v2, v39, v2
	v_add_f32_e32 v2, v42, v2
	v_pk_mul_f32 v[46:47], v[44:45], v[44:45]
	v_add_f32_e32 v2, v43, v2
	v_add_f32_e32 v2, v46, v2
	v_pk_mul_f32 v[50:51], v[48:49], v[48:49]
	v_add_f32_e32 v2, v47, v2
	v_add_f32_e32 v2, v50, v2
	v_pk_mul_f32 v[54:55], v[52:53], v[52:53]
	v_add_f32_e32 v2, v51, v2
	v_add_f32_e32 v2, v54, v2
	v_pk_mul_f32 v[62:63], v[60:61], v[60:61]
	v_add_f32_e32 v2, v55, v2
	v_add_f32_e32 v2, v62, v2
	v_pk_mul_f32 v[64:65], v[56:57], v[56:57]
	v_add_f32_e32 v2, v63, v2
	v_add_f32_e32 v2, v64, v2
	v_pk_mul_f32 v[0:1], v[58:59], v[58:59]
	v_add_f32_e32 v2, v65, v2
	v_add_f32_e32 v0, v0, v2
	v_add_f32_e32 v0, v1, v0
	ds_bpermute_b32 v1, v182, v0
	v_mov_b64_e32 v[14:15], s[6:7]
	v_readlane_b32 s43, v253, 19
	v_readlane_b32 s44, v253, 20
	v_readlane_b32 s45, v253, 21
	s_waitcnt lgkmcnt(0)
	v_add_f32_e32 v0, v0, v1
	ds_bpermute_b32 v1, v181, v0
	v_readlane_b32 s46, v253, 22
	v_readlane_b32 s47, v253, 23
	v_readlane_b32 s50, v253, 26
	v_readlane_b32 s51, v253, 27
	s_waitcnt lgkmcnt(0)
	v_add_f32_e32 v0, v0, v1
	v_fmamk_f32 v0, v0, 0x3c000000, v193
	v_cmp_gt_f32_e32 vcc, s79, v0
	v_mul_f32_e32 v1, 0x4b800000, v0
	s_nop 0
	v_cndmask_b32_e32 v0, v0, v1, vcc
	v_rsq_f32_e32 v0, v0
	s_nop 0
	v_mul_f32_e32 v1, 0x45800000, v0
	v_cndmask_b32_e32 v0, v0, v1, vcc
	v_mul_f32_e32 v6, v203, v0
	v_pk_mul_f32 v[0:1], v[4:5], v[6:7] op_sel_hi:[1,0]
	v_pk_mul_f32 v[2:3], v[8:9], v[6:7] op_sel_hi:[1,0]
	ds_write_b128 v112, v[0:3]
	v_pk_mul_f32 v[0:1], v[12:13], v[6:7] op_sel_hi:[1,0]
	v_pk_mul_f32 v[2:3], v[16:17], v[6:7] op_sel_hi:[1,0]
	ds_write_b128 v112, v[0:3] offset:64
	v_pk_mul_f32 v[0:1], v[20:21], v[6:7] op_sel_hi:[1,0]
	v_pk_mul_f32 v[2:3], v[24:25], v[6:7] op_sel_hi:[1,0]
	ds_write_b128 v112, v[0:3] offset:128
	v_pk_mul_f32 v[0:1], v[28:29], v[6:7] op_sel_hi:[1,0]
	v_pk_mul_f32 v[2:3], v[32:33], v[6:7] op_sel_hi:[1,0]
	ds_write_b128 v112, v[0:3] offset:192
	v_pk_mul_f32 v[0:1], v[36:37], v[6:7] op_sel_hi:[1,0]
	v_pk_mul_f32 v[2:3], v[40:41], v[6:7] op_sel_hi:[1,0]
	ds_write_b128 v112, v[0:3] offset:256
	v_pk_mul_f32 v[0:1], v[44:45], v[6:7] op_sel_hi:[1,0]
	v_pk_mul_f32 v[2:3], v[48:49], v[6:7] op_sel_hi:[1,0]
	ds_write_b128 v112, v[0:3] offset:320
	v_pk_mul_f32 v[0:1], v[52:53], v[6:7] op_sel_hi:[1,0]
	v_pk_mul_f32 v[2:3], v[60:61], v[6:7] op_sel_hi:[1,0]
	ds_write_b128 v112, v[0:3] offset:384
	v_pk_mul_f32 v[0:1], v[56:57], v[6:7] op_sel_hi:[1,0]
	v_pk_mul_f32 v[2:3], v[58:59], v[6:7] op_sel_hi:[1,0]
	v_and_b32_e32 v5, 0x78, v186
	v_add_u32_e32 v16, s20, v185
	ds_write_b128 v112, v[0:3] offset:448
	v_or_b32_e32 v4, s22, v5
	v_mad_i64_i32 v[0:1], s[22:23], v16, s0, v[14:15]
	v_lshl_add_u64 v[0:1], v[0:1], 0, s[70:71]
	v_lshlrev_b32_e32 v160, 1, v5
	v_lshl_add_u64 v[0:1], v[0:1], 0, v[160:161]
	v_add_co_u32_e32 v0, vcc, s3, v0
	s_waitcnt lgkmcnt(0)
	s_nop 0
	v_addc_co_u32_e32 v1, vcc, 0, v1, vcc
	s_barrier
	global_load_dwordx4 v[0:3], v[0:1], off
	v_mul_lo_u32 v6, v185, s52
	v_lshlrev_b32_e32 v20, 2, v5
	v_mov_b32_e32 v5, v161
	v_add3_u32 v6, s17, v6, v20
	v_lshl_add_u64 v[12:13], v[4:5], 2, s[48:49]
	v_ashrrev_i32_e32 v17, 31, v16
	s_waitcnt vmcnt(1)
	global_load_dwordx4 v[8:11], v[12:13], off offset:16
	global_load_dwordx4 v[26:29], v[12:13], off
	v_add_u32_e32 v64, s20, v180
	v_mad_i64_i32 v[68:69], s[100:101], v64, s0, v[14:15]
	v_lshl_add_u64 v[70:71], v[68:69], 0, s[70:71]
	v_lshl_add_u64 v[72:73], v[70:71], 0, v[160:161]
	v_add_co_u32_e32 v72, vcc, s3, v72
	s_nop 1
	v_addc_co_u32_e32 v73, vcc, 0, v73, vcc
	global_load_dwordx4 v[74:77], v[72:73], off
	global_load_dwordx4 v[68:71], v[12:13], off offset:16
	global_load_dwordx4 v[78:81], v[12:13], off
	v_add_u32_e32 v72, s20, v179
	v_mad_i64_i32 v[84:85], s[100:101], v72, s0, v[14:15]
	v_lshl_add_u64 v[86:87], v[84:85], 0, s[70:71]
	v_lshl_add_u64 v[88:89], v[86:87], 0, v[160:161]
	v_add_co_u32_e32 v88, vcc, s3, v88
	s_nop 1
	v_addc_co_u32_e32 v89, vcc, 0, v89, vcc
	global_load_dwordx4 v[90:93], v[88:89], off
	global_load_dwordx4 v[84:87], v[12:13], off offset:16
	global_load_dwordx4 v[110:113], v[12:13], off
	v_add_u32_e32 v88, s20, v178
	v_mad_i64_i32 v[116:117], s[100:101], v88, s0, v[14:15]
	v_lshl_add_u64 v[118:119], v[116:117], 0, s[70:71]
	v_lshl_add_u64 v[120:121], v[118:119], 0, v[160:161]
	v_add_co_u32_e32 v120, vcc, s3, v120
	s_nop 1
	v_addc_co_u32_e32 v121, vcc, 0, v121, vcc
	global_load_dwordx4 v[122:125], v[120:121], off
	global_load_dwordx4 v[116:119], v[12:13], off offset:16
	global_load_dwordx4 v[12:15], v[12:13], off
	s_waitcnt vmcnt(11)
	v_and_b32_e32 v21, 0xffff0000, v0
	v_lshlrev_b32_e32 v0, 16, v0
	v_mul_f32_e32 v4, 0xbfb8aa3b, v0
	v_exp_f32_e32 v18, v4
	ds_read_b128 v[22:25], v6
	ds_read_b128 v[4:7], v6 offset:16
	s_nop 0
	s_nop 0
	v_mul_f32_e32 v19, 0xbfb8aa3b, v21
	v_exp_f32_e32 v19, v19
	s_waitcnt  lgkmcnt(0)
	s_waitcnt vmcnt(10)
	v_pk_mul_f32 v[4:5], v[4:5], v[8:9]
	v_pk_add_f32 v[18:19], v[18:19], 1.0 op_sel_hi:[1,0]
	s_waitcnt vmcnt(9)
	v_pk_mul_f32 v[22:23], v[22:23], v[26:27]
	v_div_scale_f32 v26, s[22:23], v19, v19, v21
	v_rcp_f32_e32 v27, v26
	v_pk_mul_f32 v[6:7], v[6:7], v[10:11]
	v_fma_f32 v30, -v26, v27, 1.0
	v_fmac_f32_e32 v27, v30, v27
	v_div_scale_f32 v30, vcc, v21, v19, v21
	v_mul_f32_e32 v31, v30, v27
	v_fma_f32 v32, -v26, v31, v30
	v_fmac_f32_e32 v31, v32, v27
	v_fma_f32 v26, -v26, v31, v30
	v_div_fmas_f32 v26, v26, v27, v31
	v_div_fixup_f32 v19, v26, v19, v21
	v_div_scale_f32 v21, s[22:23], v18, v18, v0
	v_rcp_f32_e32 v26, v21
	s_nop 0
	v_fma_f32 v27, -v21, v26, 1.0
	v_fmac_f32_e32 v26, v27, v26
	v_div_scale_f32 v27, vcc, v0, v18, v0
	v_mul_f32_e32 v30, v27, v26
	v_fma_f32 v31, -v21, v30, v27
	v_fmac_f32_e32 v30, v31, v26
	v_fma_f32 v21, -v21, v30, v27
	v_div_fmas_f32 v21, v21, v26, v30
	v_div_fixup_f32 v18, v21, v18, v0
	v_and_b32_e32 v21, 0xffff0000, v1
	v_lshlrev_b32_e32 v26, 16, v1
	v_mul_f32_e32 v0, 0xbfb8aa3b, v26
	v_mul_f32_e32 v1, 0xbfb8aa3b, v21
	v_exp_f32_e32 v0, v0
	v_exp_f32_e32 v1, v1
	v_pk_mul_f32 v[18:19], v[22:23], v[18:19]
	v_pk_mul_f32 v[22:23], v[24:25], v[28:29]
	v_pk_add_f32 v[0:1], v[0:1], 1.0 op_sel_hi:[1,0]
	s_nop 0
	v_div_scale_f32 v24, s[22:23], v1, v1, v21
	v_rcp_f32_e32 v25, v24
	s_nop 0
	v_fma_f32 v27, -v24, v25, 1.0
	v_fmac_f32_e32 v25, v27, v25
	v_div_scale_f32 v27, vcc, v21, v1, v21
	v_mul_f32_e32 v28, v27, v25
	v_fma_f32 v29, -v24, v28, v27
	v_fmac_f32_e32 v28, v29, v25
	v_fma_f32 v24, -v24, v28, v27
	v_div_fmas_f32 v24, v24, v25, v28
	v_div_fixup_f32 v1, v24, v1, v21
	v_div_scale_f32 v21, s[22:23], v0, v0, v26
	v_rcp_f32_e32 v24, v21
	s_nop 0
	v_fma_f32 v25, -v21, v24, 1.0
	v_fmac_f32_e32 v24, v25, v24
	v_div_scale_f32 v25, vcc, v26, v0, v26
	v_mul_f32_e32 v27, v25, v24
	v_fma_f32 v28, -v21, v27, v25
	v_fmac_f32_e32 v27, v28, v24
	v_fma_f32 v21, -v21, v27, v25
	v_div_fmas_f32 v21, v21, v24, v27
	v_div_fixup_f32 v0, v21, v0, v26
	v_and_b32_e32 v21, 0xffff0000, v2
	v_lshlrev_b32_e32 v2, 16, v2
	v_pk_mul_f32 v[0:1], v[22:23], v[0:1]
	v_mul_f32_e32 v22, 0xbfb8aa3b, v2
	v_mul_f32_e32 v8, 0xbfb8aa3b, v21
	v_exp_f32_e32 v22, v22
	v_exp_f32_e32 v23, v8
	s_nop 0
	v_pk_add_f32 v[8:9], v[22:23], 1.0 op_sel_hi:[1,0]
	s_nop 0
	v_div_scale_f32 v22, s[22:23], v9, v9, v21
	v_rcp_f32_e32 v23, v22
	s_nop 0
	v_fma_f32 v24, -v22, v23, 1.0
	v_fmac_f32_e32 v23, v24, v23
	v_div_scale_f32 v24, vcc, v21, v9, v21
	v_mul_f32_e32 v25, v24, v23
	v_fma_f32 v26, -v22, v25, v24
	v_fmac_f32_e32 v25, v26, v23
	v_fma_f32 v22, -v22, v25, v24
	v_div_fmas_f32 v22, v22, v23, v25
	v_div_fixup_f32 v9, v22, v9, v21
	v_div_scale_f32 v21, s[22:23], v8, v8, v2
	v_rcp_f32_e32 v22, v21
	s_nop 0
	v_fma_f32 v23, -v21, v22, 1.0
	v_fmac_f32_e32 v22, v23, v22
	v_div_scale_f32 v23, vcc, v2, v8, v2
	v_mul_f32_e32 v24, v23, v22
	v_fma_f32 v25, -v21, v24, v23
	v_fmac_f32_e32 v24, v25, v22
	v_fma_f32 v21, -v21, v24, v23
	v_div_fmas_f32 v21, v21, v22, v24
	v_div_fixup_f32 v8, v21, v8, v2
	v_pk_mul_f32 v[4:5], v[8:9], v[4:5]
	v_and_b32_e32 v8, 0xffff0000, v3
	v_lshlrev_b32_e32 v9, 16, v3
	v_mul_f32_e32 v2, 0xbfb8aa3b, v9
	v_mul_f32_e32 v3, 0xbfb8aa3b, v8
	v_exp_f32_e32 v2, v2
	v_exp_f32_e32 v3, v3
	s_nop 0
	v_pk_add_f32 v[2:3], v[2:3], 1.0 op_sel_hi:[1,0]
	s_nop 0
	v_div_scale_f32 v10, s[22:23], v3, v3, v8
	v_rcp_f32_e32 v11, v10
	s_nop 0
	v_fma_f32 v21, -v10, v11, 1.0
	v_fmac_f32_e32 v11, v21, v11
	v_div_scale_f32 v21, vcc, v8, v3, v8
	v_mul_f32_e32 v22, v21, v11
	v_fma_f32 v23, -v10, v22, v21
	v_fmac_f32_e32 v22, v23, v11
	v_fma_f32 v10, -v10, v22, v21
	v_div_fmas_f32 v10, v10, v11, v22
	v_div_fixup_f32 v3, v10, v3, v8
	v_div_scale_f32 v8, s[22:23], v2, v2, v9
	v_rcp_f32_e32 v10, v8
	s_nop 0
	v_fma_f32 v11, -v8, v10, 1.0
	v_fmac_f32_e32 v10, v11, v10
	v_div_scale_f32 v11, vcc, v9, v2, v9
	v_mul_f32_e32 v21, v11, v10
	v_fma_f32 v22, -v8, v21, v11
	v_fmac_f32_e32 v21, v22, v10
	v_fma_f32 v8, -v8, v21, v11
	v_div_fmas_f32 v8, v8, v10, v21
	v_div_fixup_f32 v2, v8, v2, v9
	v_pk_mul_f32 v[2:3], v[2:3], v[6:7]
	v_cvt_pk_bf16_f32 v4, v4, v5
	v_cvt_pk_bf16_f32 v2, v2, v3
	v_mov_b32_e32 v3, v2
	v_mov_b32_e32 v2, v4
	v_lshlrev_b64 v[4:5], 12, v[16:17]
	v_lshl_add_u64 v[4:5], s[30:31], 0, v[4:5]
	v_lshl_add_u64 v[4:5], v[4:5], 0, s[70:71]
	v_lshl_add_u64 v[4:5], v[4:5], 0, v[160:161]
	v_cvt_pk_bf16_f32 v18, v18, v19
	v_cvt_pk_bf16_f32 v0, v0, v1
	v_add_co_u32_e32 v4, vcc, s21, v4
	v_mov_b32_e32 v1, v0
	v_mov_b32_e32 v0, v18
	v_addc_co_u32_e32 v5, vcc, 0, v5, vcc
	v_add_u32_e32 v16, s20, v180
	global_store_dwordx4 v[4:5], v[0:3], off offset:2048
	v_mul_lo_u32 v4, v180, s52
	v_add3_u32 v4, s17, v4, v20
	s_nop 0
	s_nop 0
	s_nop 0
	s_nop 0
	v_ashrrev_i32_e32 v17, 31, v16
	s_nop 0
	s_nop 0
	s_nop 0
	s_waitcnt vmcnt(9)
	v_and_b32_e32 v21, 0xffff0000, v74
	v_lshlrev_b32_e32 v0, 16, v74
	v_mul_f32_e32 v5, 0xbfb8aa3b, v0
	v_exp_f32_e32 v18, v5
	ds_read_b128 v[22:25], v4
	ds_read_b128 v[4:7], v4 offset:16
	s_nop 0
	s_nop 0
	v_mul_f32_e32 v19, 0xbfb8aa3b, v21
	v_exp_f32_e32 v19, v19
	s_waitcnt  lgkmcnt(0)
	s_waitcnt vmcnt(8)
	v_pk_mul_f32 v[4:5], v[4:5], v[68:69]
	v_pk_add_f32 v[18:19], v[18:19], 1.0 op_sel_hi:[1,0]
	s_waitcnt vmcnt(7)
	v_pk_mul_f32 v[22:23], v[22:23], v[78:79]
	v_div_scale_f32 v26, s[22:23], v19, v19, v21
	v_rcp_f32_e32 v27, v26
	v_pk_mul_f32 v[6:7], v[6:7], v[70:71]
	v_fma_f32 v30, -v26, v27, 1.0
	v_fmac_f32_e32 v27, v30, v27
	v_div_scale_f32 v30, vcc, v21, v19, v21
	v_mul_f32_e32 v31, v30, v27
	v_fma_f32 v32, -v26, v31, v30
	v_fmac_f32_e32 v31, v32, v27
	v_fma_f32 v26, -v26, v31, v30
	v_div_fmas_f32 v26, v26, v27, v31
	v_div_fixup_f32 v19, v26, v19, v21
	v_div_scale_f32 v21, s[22:23], v18, v18, v0
	v_rcp_f32_e32 v26, v21
	s_nop 0
	v_fma_f32 v27, -v21, v26, 1.0
	v_fmac_f32_e32 v26, v27, v26
	v_div_scale_f32 v27, vcc, v0, v18, v0
	v_mul_f32_e32 v30, v27, v26
	v_fma_f32 v31, -v21, v30, v27
	v_fmac_f32_e32 v30, v31, v26
	v_fma_f32 v21, -v21, v30, v27
	v_div_fmas_f32 v21, v21, v26, v30
	v_div_fixup_f32 v18, v21, v18, v0
	v_and_b32_e32 v21, 0xffff0000, v75
	v_lshlrev_b32_e32 v26, 16, v75
	v_mul_f32_e32 v0, 0xbfb8aa3b, v26
	v_mul_f32_e32 v1, 0xbfb8aa3b, v21
	v_exp_f32_e32 v0, v0
	v_exp_f32_e32 v1, v1
	v_pk_mul_f32 v[18:19], v[22:23], v[18:19]
	v_pk_mul_f32 v[22:23], v[24:25], v[80:81]
	v_pk_add_f32 v[0:1], v[0:1], 1.0 op_sel_hi:[1,0]
	s_nop 0
	v_div_scale_f32 v24, s[22:23], v1, v1, v21
	v_rcp_f32_e32 v25, v24
	s_nop 0
	v_fma_f32 v27, -v24, v25, 1.0
	v_fmac_f32_e32 v25, v27, v25
	v_div_scale_f32 v27, vcc, v21, v1, v21
	v_mul_f32_e32 v28, v27, v25
	v_fma_f32 v29, -v24, v28, v27
	v_fmac_f32_e32 v28, v29, v25
	v_fma_f32 v24, -v24, v28, v27
	v_div_fmas_f32 v24, v24, v25, v28
	v_div_fixup_f32 v1, v24, v1, v21
	v_div_scale_f32 v21, s[22:23], v0, v0, v26
	v_rcp_f32_e32 v24, v21
	s_nop 0
	v_fma_f32 v25, -v21, v24, 1.0
	v_fmac_f32_e32 v24, v25, v24
	v_div_scale_f32 v25, vcc, v26, v0, v26
	v_mul_f32_e32 v27, v25, v24
	v_fma_f32 v28, -v21, v27, v25
	v_fmac_f32_e32 v27, v28, v24
	v_fma_f32 v21, -v21, v27, v25
	v_div_fmas_f32 v21, v21, v24, v27
	v_div_fixup_f32 v0, v21, v0, v26
	v_and_b32_e32 v21, 0xffff0000, v76
	v_lshlrev_b32_e32 v2, 16, v76
	v_pk_mul_f32 v[0:1], v[22:23], v[0:1]
	v_mul_f32_e32 v22, 0xbfb8aa3b, v2
	v_mul_f32_e32 v8, 0xbfb8aa3b, v21
	v_exp_f32_e32 v22, v22
	v_exp_f32_e32 v23, v8
	s_nop 0
	v_pk_add_f32 v[8:9], v[22:23], 1.0 op_sel_hi:[1,0]
	s_nop 0
	v_div_scale_f32 v22, s[22:23], v9, v9, v21
	v_rcp_f32_e32 v23, v22
	s_nop 0
	v_fma_f32 v24, -v22, v23, 1.0
	v_fmac_f32_e32 v23, v24, v23
	v_div_scale_f32 v24, vcc, v21, v9, v21
	v_mul_f32_e32 v25, v24, v23
	v_fma_f32 v26, -v22, v25, v24
	v_fmac_f32_e32 v25, v26, v23
	v_fma_f32 v22, -v22, v25, v24
	v_div_fmas_f32 v22, v22, v23, v25
	v_div_fixup_f32 v9, v22, v9, v21
	v_div_scale_f32 v21, s[22:23], v8, v8, v2
	v_rcp_f32_e32 v22, v21
	s_nop 0
	v_fma_f32 v23, -v21, v22, 1.0
	v_fmac_f32_e32 v22, v23, v22
	v_div_scale_f32 v23, vcc, v2, v8, v2
	v_mul_f32_e32 v24, v23, v22
	v_fma_f32 v25, -v21, v24, v23
	v_fmac_f32_e32 v24, v25, v22
	v_fma_f32 v21, -v21, v24, v23
	v_div_fmas_f32 v21, v21, v22, v24
	v_div_fixup_f32 v8, v21, v8, v2
	v_pk_mul_f32 v[4:5], v[8:9], v[4:5]
	v_and_b32_e32 v8, 0xffff0000, v77
	v_lshlrev_b32_e32 v9, 16, v77
	v_mul_f32_e32 v2, 0xbfb8aa3b, v9
	v_mul_f32_e32 v3, 0xbfb8aa3b, v8
	v_exp_f32_e32 v2, v2
	v_exp_f32_e32 v3, v3
	s_nop 0
	v_pk_add_f32 v[2:3], v[2:3], 1.0 op_sel_hi:[1,0]
	s_nop 0
	v_div_scale_f32 v10, s[22:23], v3, v3, v8
	v_rcp_f32_e32 v11, v10
	s_nop 0
	v_fma_f32 v21, -v10, v11, 1.0
	v_fmac_f32_e32 v11, v21, v11
	v_div_scale_f32 v21, vcc, v8, v3, v8
	v_mul_f32_e32 v22, v21, v11
	v_fma_f32 v23, -v10, v22, v21
	v_fmac_f32_e32 v22, v23, v11
	v_fma_f32 v10, -v10, v22, v21
	v_div_fmas_f32 v10, v10, v11, v22
	v_div_fixup_f32 v3, v10, v3, v8
	v_div_scale_f32 v8, s[22:23], v2, v2, v9
	v_rcp_f32_e32 v10, v8
	s_nop 0
	v_fma_f32 v11, -v8, v10, 1.0
	v_fmac_f32_e32 v10, v11, v10
	v_div_scale_f32 v11, vcc, v9, v2, v9
	v_mul_f32_e32 v21, v11, v10
	v_fma_f32 v22, -v8, v21, v11
	v_fmac_f32_e32 v21, v22, v10
	v_fma_f32 v8, -v8, v21, v11
	v_div_fmas_f32 v8, v8, v10, v21
	v_div_fixup_f32 v2, v8, v2, v9
	v_pk_mul_f32 v[2:3], v[2:3], v[6:7]
	v_cvt_pk_bf16_f32 v4, v4, v5
	v_cvt_pk_bf16_f32 v2, v2, v3
	v_mov_b32_e32 v3, v2
	v_mov_b32_e32 v2, v4
	v_lshlrev_b64 v[4:5], 12, v[16:17]
	v_lshl_add_u64 v[4:5], s[30:31], 0, v[4:5]
	v_lshl_add_u64 v[4:5], v[4:5], 0, s[70:71]
	v_lshl_add_u64 v[4:5], v[4:5], 0, v[160:161]
	v_cvt_pk_bf16_f32 v18, v18, v19
	v_cvt_pk_bf16_f32 v0, v0, v1
	v_add_co_u32_e32 v4, vcc, s21, v4
	v_mov_b32_e32 v1, v0
	v_mov_b32_e32 v0, v18
	v_addc_co_u32_e32 v5, vcc, 0, v5, vcc
	v_add_u32_e32 v16, s20, v179
	global_store_dwordx4 v[4:5], v[0:3], off offset:2048
	v_mul_lo_u32 v4, v179, s52
	v_add3_u32 v4, s17, v4, v20
	s_nop 0
	s_nop 0
	s_nop 0
	s_nop 0
	v_ashrrev_i32_e32 v17, 31, v16
	s_nop 0
	s_nop 0
	s_nop 0
	s_waitcnt vmcnt(7)
	v_and_b32_e32 v21, 0xffff0000, v90
	v_lshlrev_b32_e32 v0, 16, v90
	v_mul_f32_e32 v5, 0xbfb8aa3b, v0
	v_exp_f32_e32 v18, v5
	ds_read_b128 v[22:25], v4
	ds_read_b128 v[4:7], v4 offset:16
	s_nop 0
	s_nop 0
	v_mul_f32_e32 v19, 0xbfb8aa3b, v21
	v_exp_f32_e32 v19, v19
	s_waitcnt  lgkmcnt(0)
	s_waitcnt vmcnt(6)
	v_pk_mul_f32 v[4:5], v[4:5], v[84:85]
	v_pk_add_f32 v[18:19], v[18:19], 1.0 op_sel_hi:[1,0]
	s_waitcnt vmcnt(5)
	v_pk_mul_f32 v[22:23], v[22:23], v[110:111]
	v_div_scale_f32 v26, s[22:23], v19, v19, v21
	v_rcp_f32_e32 v27, v26
	v_pk_mul_f32 v[6:7], v[6:7], v[86:87]
	v_fma_f32 v30, -v26, v27, 1.0
	v_fmac_f32_e32 v27, v30, v27
	v_div_scale_f32 v30, vcc, v21, v19, v21
	v_mul_f32_e32 v31, v30, v27
	v_fma_f32 v32, -v26, v31, v30
	v_fmac_f32_e32 v31, v32, v27
	v_fma_f32 v26, -v26, v31, v30
	v_div_fmas_f32 v26, v26, v27, v31
	v_div_fixup_f32 v19, v26, v19, v21
	v_div_scale_f32 v21, s[22:23], v18, v18, v0
	v_rcp_f32_e32 v26, v21
	s_nop 0
	v_fma_f32 v27, -v21, v26, 1.0
	v_fmac_f32_e32 v26, v27, v26
	v_div_scale_f32 v27, vcc, v0, v18, v0
	v_mul_f32_e32 v30, v27, v26
	v_fma_f32 v31, -v21, v30, v27
	v_fmac_f32_e32 v30, v31, v26
	v_fma_f32 v21, -v21, v30, v27
	v_div_fmas_f32 v21, v21, v26, v30
	v_div_fixup_f32 v18, v21, v18, v0
	v_and_b32_e32 v21, 0xffff0000, v91
	v_lshlrev_b32_e32 v26, 16, v91
	v_mul_f32_e32 v0, 0xbfb8aa3b, v26
	v_mul_f32_e32 v1, 0xbfb8aa3b, v21
	v_exp_f32_e32 v0, v0
	v_exp_f32_e32 v1, v1
	v_pk_mul_f32 v[18:19], v[22:23], v[18:19]
	v_pk_mul_f32 v[22:23], v[24:25], v[112:113]
	v_pk_add_f32 v[0:1], v[0:1], 1.0 op_sel_hi:[1,0]
	s_nop 0
	v_div_scale_f32 v24, s[22:23], v1, v1, v21
	v_rcp_f32_e32 v25, v24
	s_nop 0
	v_fma_f32 v27, -v24, v25, 1.0
	v_fmac_f32_e32 v25, v27, v25
	v_div_scale_f32 v27, vcc, v21, v1, v21
	v_mul_f32_e32 v28, v27, v25
	v_fma_f32 v29, -v24, v28, v27
	v_fmac_f32_e32 v28, v29, v25
	v_fma_f32 v24, -v24, v28, v27
	v_div_fmas_f32 v24, v24, v25, v28
	v_div_fixup_f32 v1, v24, v1, v21
	v_div_scale_f32 v21, s[22:23], v0, v0, v26
	v_rcp_f32_e32 v24, v21
	s_nop 0
	v_fma_f32 v25, -v21, v24, 1.0
	v_fmac_f32_e32 v24, v25, v24
	v_div_scale_f32 v25, vcc, v26, v0, v26
	v_mul_f32_e32 v27, v25, v24
	v_fma_f32 v28, -v21, v27, v25
	v_fmac_f32_e32 v27, v28, v24
	v_fma_f32 v21, -v21, v27, v25
	v_div_fmas_f32 v21, v21, v24, v27
	v_div_fixup_f32 v0, v21, v0, v26
	v_and_b32_e32 v21, 0xffff0000, v92
	v_lshlrev_b32_e32 v2, 16, v92
	v_pk_mul_f32 v[0:1], v[22:23], v[0:1]
	v_mul_f32_e32 v22, 0xbfb8aa3b, v2
	v_mul_f32_e32 v8, 0xbfb8aa3b, v21
	v_exp_f32_e32 v22, v22
	v_exp_f32_e32 v23, v8
	s_nop 0
	v_pk_add_f32 v[8:9], v[22:23], 1.0 op_sel_hi:[1,0]
	s_nop 0
	v_div_scale_f32 v22, s[22:23], v9, v9, v21
	v_rcp_f32_e32 v23, v22
	s_nop 0
	v_fma_f32 v24, -v22, v23, 1.0
	v_fmac_f32_e32 v23, v24, v23
	v_div_scale_f32 v24, vcc, v21, v9, v21
	v_mul_f32_e32 v25, v24, v23
	v_fma_f32 v26, -v22, v25, v24
	v_fmac_f32_e32 v25, v26, v23
	v_fma_f32 v22, -v22, v25, v24
	v_div_fmas_f32 v22, v22, v23, v25
	v_div_fixup_f32 v9, v22, v9, v21
	v_div_scale_f32 v21, s[22:23], v8, v8, v2
	v_rcp_f32_e32 v22, v21
	s_nop 0
	v_fma_f32 v23, -v21, v22, 1.0
	v_fmac_f32_e32 v22, v23, v22
	v_div_scale_f32 v23, vcc, v2, v8, v2
	v_mul_f32_e32 v24, v23, v22
	v_fma_f32 v25, -v21, v24, v23
	v_fmac_f32_e32 v24, v25, v22
	v_fma_f32 v21, -v21, v24, v23
	v_div_fmas_f32 v21, v21, v22, v24
	v_div_fixup_f32 v8, v21, v8, v2
	v_pk_mul_f32 v[4:5], v[8:9], v[4:5]
	v_and_b32_e32 v8, 0xffff0000, v93
	v_lshlrev_b32_e32 v9, 16, v93
	v_mul_f32_e32 v2, 0xbfb8aa3b, v9
	v_mul_f32_e32 v3, 0xbfb8aa3b, v8
	v_exp_f32_e32 v2, v2
	v_exp_f32_e32 v3, v3
	s_nop 0
	v_pk_add_f32 v[2:3], v[2:3], 1.0 op_sel_hi:[1,0]
	s_nop 0
	v_div_scale_f32 v10, s[22:23], v3, v3, v8
	v_rcp_f32_e32 v11, v10
	s_nop 0
	v_fma_f32 v21, -v10, v11, 1.0
	v_fmac_f32_e32 v11, v21, v11
	v_div_scale_f32 v21, vcc, v8, v3, v8
	v_mul_f32_e32 v22, v21, v11
	v_fma_f32 v23, -v10, v22, v21
	v_fmac_f32_e32 v22, v23, v11
	v_fma_f32 v10, -v10, v22, v21
	v_div_fmas_f32 v10, v10, v11, v22
	v_div_fixup_f32 v3, v10, v3, v8
	v_div_scale_f32 v8, s[22:23], v2, v2, v9
	v_rcp_f32_e32 v10, v8
	s_nop 0
	v_fma_f32 v11, -v8, v10, 1.0
	v_fmac_f32_e32 v10, v11, v10
	v_div_scale_f32 v11, vcc, v9, v2, v9
	v_mul_f32_e32 v21, v11, v10
	v_fma_f32 v22, -v8, v21, v11
	v_fmac_f32_e32 v21, v22, v10
	v_fma_f32 v8, -v8, v21, v11
	v_div_fmas_f32 v8, v8, v10, v21
	v_div_fixup_f32 v2, v8, v2, v9
	v_pk_mul_f32 v[2:3], v[2:3], v[6:7]
	v_cvt_pk_bf16_f32 v4, v4, v5
	v_cvt_pk_bf16_f32 v2, v2, v3
	v_mov_b32_e32 v3, v2
	v_mov_b32_e32 v2, v4
	v_lshlrev_b64 v[4:5], 12, v[16:17]
	v_lshl_add_u64 v[4:5], s[30:31], 0, v[4:5]
	v_lshl_add_u64 v[4:5], v[4:5], 0, s[70:71]
	v_lshl_add_u64 v[4:5], v[4:5], 0, v[160:161]
	v_cvt_pk_bf16_f32 v18, v18, v19
	v_cvt_pk_bf16_f32 v0, v0, v1
	v_add_co_u32_e32 v4, vcc, s21, v4
	v_mov_b32_e32 v1, v0
	v_mov_b32_e32 v0, v18
	v_addc_co_u32_e32 v5, vcc, 0, v5, vcc
	v_add_u32_e32 v16, s20, v178
	global_store_dwordx4 v[4:5], v[0:3], off offset:2048
	v_mul_lo_u32 v4, v178, s52
	v_add3_u32 v4, s17, v4, v20
	s_nop 0
	s_nop 0
	s_nop 0
	s_nop 0
	v_ashrrev_i32_e32 v17, 31, v16
	s_nop 0
	s_nop 0
	s_nop 0
	s_waitcnt vmcnt(5)
	v_and_b32_e32 v24, 0xffff0000, v122
	v_lshlrev_b32_e32 v0, 16, v122
	v_mul_f32_e32 v5, 0xbfb8aa3b, v0
	v_exp_f32_e32 v22, v5
	ds_read_b128 v[18:21], v4
	ds_read_b128 v[4:7], v4 offset:16
	s_nop 0
	s_nop 0
	s_nop 0
	s_waitcnt  lgkmcnt(0)
	s_waitcnt vmcnt(4)
	v_pk_mul_f32 v[4:5], v[4:5], v[116:117]
	s_waitcnt vmcnt(3)
	v_pk_mul_f32 v[12:13], v[18:19], v[12:13]
	v_mul_f32_e32 v18, 0xbfb8aa3b, v24
	v_exp_f32_e32 v23, v18
	v_pk_mul_f32 v[14:15], v[20:21], v[14:15]
	v_pk_mul_f32 v[6:7], v[6:7], v[118:119]
	v_pk_add_f32 v[18:19], v[22:23], 1.0 op_sel_hi:[1,0]
	s_nop 0
	v_div_scale_f32 v22, s[20:21], v19, v19, v24
	v_rcp_f32_e32 v23, v22
	s_nop 0
	v_fma_f32 v25, -v22, v23, 1.0
	v_fmac_f32_e32 v23, v25, v23
	v_div_scale_f32 v25, vcc, v24, v19, v24
	v_mul_f32_e32 v26, v25, v23
	v_fma_f32 v27, -v22, v26, v25
	v_fmac_f32_e32 v26, v27, v23
	v_fma_f32 v22, -v22, v26, v25
	v_div_fmas_f32 v22, v22, v23, v26
	v_div_fixup_f32 v19, v22, v19, v24
	v_div_scale_f32 v22, s[20:21], v18, v18, v0
	v_rcp_f32_e32 v23, v22
	s_nop 0
	v_fma_f32 v24, -v22, v23, 1.0
	v_fmac_f32_e32 v23, v24, v23
	v_div_scale_f32 v24, vcc, v0, v18, v0
	v_mul_f32_e32 v25, v24, v23
	v_fma_f32 v26, -v22, v25, v24
	v_fmac_f32_e32 v25, v26, v23
	v_fma_f32 v22, -v22, v25, v24
	v_div_fmas_f32 v22, v22, v23, v25
	v_div_fixup_f32 v18, v22, v18, v0
	v_pk_mul_f32 v[12:13], v[12:13], v[18:19]
	v_and_b32_e32 v18, 0xffff0000, v123
	v_lshlrev_b32_e32 v19, 16, v123
	v_mul_f32_e32 v0, 0xbfb8aa3b, v19
	v_mul_f32_e32 v1, 0xbfb8aa3b, v18
	v_exp_f32_e32 v0, v0
	v_exp_f32_e32 v1, v1
	s_nop 0
	v_pk_add_f32 v[0:1], v[0:1], 1.0 op_sel_hi:[1,0]
	s_nop 0
	v_div_scale_f32 v20, s[20:21], v1, v1, v18
	v_rcp_f32_e32 v21, v20
	s_nop 0
	v_fma_f32 v22, -v20, v21, 1.0
	v_fmac_f32_e32 v21, v22, v21
	v_div_scale_f32 v22, vcc, v18, v1, v18
	v_mul_f32_e32 v23, v22, v21
	v_fma_f32 v24, -v20, v23, v22
	v_fmac_f32_e32 v23, v24, v21
	v_fma_f32 v20, -v20, v23, v22
	v_div_fmas_f32 v20, v20, v21, v23
	v_div_fixup_f32 v1, v20, v1, v18
	v_div_scale_f32 v18, s[20:21], v0, v0, v19
	v_rcp_f32_e32 v20, v18
	s_nop 0
	v_fma_f32 v21, -v18, v20, 1.0
	v_fmac_f32_e32 v20, v21, v20
	v_div_scale_f32 v21, vcc, v19, v0, v19
	v_mul_f32_e32 v22, v21, v20
	v_fma_f32 v23, -v18, v22, v21
	v_fmac_f32_e32 v22, v23, v20
	v_fma_f32 v18, -v18, v22, v21
	v_div_fmas_f32 v18, v18, v20, v22
	v_div_fixup_f32 v0, v18, v0, v19
	v_and_b32_e32 v18, 0xffff0000, v124
	v_lshlrev_b32_e32 v2, 16, v124
	v_pk_mul_f32 v[0:1], v[14:15], v[0:1]
	v_mul_f32_e32 v14, 0xbfb8aa3b, v2
	v_mul_f32_e32 v8, 0xbfb8aa3b, v18
	v_exp_f32_e32 v14, v14
	v_exp_f32_e32 v15, v8
	s_nop 0
	v_pk_add_f32 v[8:9], v[14:15], 1.0 op_sel_hi:[1,0]
	s_nop 0
	v_div_scale_f32 v14, s[20:21], v9, v9, v18
	v_rcp_f32_e32 v15, v14
	s_nop 0
	v_fma_f32 v19, -v14, v15, 1.0
	v_fmac_f32_e32 v15, v19, v15
	v_div_scale_f32 v19, vcc, v18, v9, v18
	v_mul_f32_e32 v20, v19, v15
	v_fma_f32 v21, -v14, v20, v19
	v_fmac_f32_e32 v20, v21, v15
	v_fma_f32 v14, -v14, v20, v19
	v_div_fmas_f32 v14, v14, v15, v20
	v_div_fixup_f32 v9, v14, v9, v18
	v_div_scale_f32 v14, s[20:21], v8, v8, v2
	v_rcp_f32_e32 v15, v14
	s_nop 0
	v_fma_f32 v18, -v14, v15, 1.0
	v_fmac_f32_e32 v15, v18, v15
	v_div_scale_f32 v18, vcc, v2, v8, v2
	v_mul_f32_e32 v19, v18, v15
	v_fma_f32 v20, -v14, v19, v18
	v_fmac_f32_e32 v19, v20, v15
	v_fma_f32 v14, -v14, v19, v18
	v_div_fmas_f32 v14, v14, v15, v19
	v_div_fixup_f32 v8, v14, v8, v2
	v_pk_mul_f32 v[4:5], v[8:9], v[4:5]
	v_and_b32_e32 v8, 0xffff0000, v125
	v_lshlrev_b32_e32 v9, 16, v125
	v_mul_f32_e32 v2, 0xbfb8aa3b, v9
	v_mul_f32_e32 v3, 0xbfb8aa3b, v8
	v_exp_f32_e32 v2, v2
	v_exp_f32_e32 v3, v3
	s_nop 0
	v_pk_add_f32 v[2:3], v[2:3], 1.0 op_sel_hi:[1,0]
	s_nop 0
	v_div_scale_f32 v10, s[20:21], v3, v3, v8
	v_rcp_f32_e32 v11, v10
	s_nop 0
	v_fma_f32 v14, -v10, v11, 1.0
	v_fmac_f32_e32 v11, v14, v11
	v_div_scale_f32 v14, vcc, v8, v3, v8
	v_mul_f32_e32 v15, v14, v11
	v_fma_f32 v18, -v10, v15, v14
	v_fmac_f32_e32 v15, v18, v11
	v_fma_f32 v10, -v10, v15, v14
	v_div_fmas_f32 v10, v10, v11, v15
	v_div_fixup_f32 v3, v10, v3, v8
	v_div_scale_f32 v8, s[20:21], v2, v2, v9
	v_rcp_f32_e32 v10, v8
	s_nop 0
	v_fma_f32 v11, -v8, v10, 1.0
	v_fmac_f32_e32 v10, v11, v10
	v_div_scale_f32 v11, vcc, v9, v2, v9
	v_mul_f32_e32 v14, v11, v10
	v_fma_f32 v15, -v8, v14, v11
	v_fmac_f32_e32 v14, v15, v10
	v_fma_f32 v8, -v8, v14, v11
	v_div_fmas_f32 v8, v8, v10, v14
	v_div_fixup_f32 v2, v8, v2, v9
	v_pk_mul_f32 v[2:3], v[2:3], v[6:7]
	v_cvt_pk_bf16_f32 v4, v4, v5
	v_cvt_pk_bf16_f32 v2, v2, v3
	v_mov_b32_e32 v3, v2
	v_mov_b32_e32 v2, v4
	v_lshlrev_b64 v[4:5], 12, v[16:17]
	v_lshl_add_u64 v[4:5], s[30:31], 0, v[4:5]
	v_lshl_add_u64 v[4:5], v[4:5], 0, s[70:71]
	v_lshl_add_u64 v[4:5], v[4:5], 0, v[160:161]
	v_cvt_pk_bf16_f32 v12, v12, v13
	v_cvt_pk_bf16_f32 v0, v0, v1
	v_add_co_u32_e32 v4, vcc, 0xcc00000, v4
	v_mov_b32_e32 v1, v0
	v_mov_b32_e32 v0, v12
	v_addc_co_u32_e32 v5, vcc, 0, v5, vcc
	global_store_dwordx4 v[4:5], v[0:3], off offset:2048
	s_barrier

.LBB0_773:
	v_xor_b32_e32 v0, 1, v151
	v_cmp_lt_i32_e32 vcc, v0, v208
	v_add_f32_e32 v2, v210, v211
	s_mov_b32 s22, 0x3fb8aa3b
	v_cndmask_b32_e32 v0, v151, v0, vcc
	v_lshlrev_b32_e32 v0, 2, v0
	ds_bpermute_b32 v3, v0, v2
	v_add_f32_e32 v1, v212, v213
	ds_bpermute_b32 v0, v0, v1
	s_mov_b32 s23, 0xc2ce8ed0
	s_mov_b32 s36, 0x42b17218
	s_waitcnt lgkmcnt(1)
	v_add_f32_e32 v2, v2, v3
	v_mul_f32_e32 v3, 0x3fb8aa3b, v2
	v_fma_f32 v4, v2, s22, -v3
	v_rndne_f32_e32 v5, v3
	v_fmac_f32_e32 v4, 0x32a5705f, v2
	v_sub_f32_e32 v3, v3, v5
	v_add_f32_e32 v3, v3, v4
	v_exp_f32_e32 v3, v3
	v_cvt_i32_f32_e32 v4, v5
	v_cmp_ngt_f32_e32 vcc, s23, v2
	s_waitcnt lgkmcnt(0)
	v_add_f32_e32 v0, v1, v0
	v_mul_f32_e32 v1, 0x3fb8aa3b, v0
	v_ldexp_f32 v3, v3, v4
	v_cndmask_b32_e32 v3, 0, v3, vcc
	v_cmp_nlt_f32_e32 vcc, s36, v2
	v_rndne_f32_e32 v4, v1
	s_movk_i32 s52, 0x210
	v_cndmask_b32_e32 v2, v200, v3, vcc
	v_fma_f32 v3, v0, s22, -v1
	v_fmac_f32_e32 v3, 0x32a5705f, v0
	v_sub_f32_e32 v1, v1, v4
	v_add_f32_e32 v1, v1, v3
	v_exp_f32_e32 v1, v1
	v_cvt_i32_f32_e32 v3, v4
	v_cmp_ngt_f32_e32 vcc, s23, v0
	s_barrier
	v_ldexp_f32 v1, v1, v3
	v_cndmask_b32_e32 v1, 0, v1, vcc
	v_cmp_nlt_f32_e32 vcc, s36, v0
	s_lshl_b32 s70, s21, 1
	s_nop 0
	v_cndmask_b32_e32 v0, v200, v1, vcc
	ds_bpermute_b32 v1, v205, v143
	v_sub_f32_e32 v0, v2, v0
	v_readlane_b32 s36, v253, 12
	v_readlane_b32 s48, v253, 24
	v_readlane_b32 s49, v253, 25
	s_waitcnt lgkmcnt(0)
	v_add_f32_e32 v1, v143, v1
	ds_bpermute_b32 v2, v141, v1
	s_mov_b32 s21, 0xcc00000
	v_readlane_b32 s37, v253, 13
	v_readlane_b32 s38, v253, 14
	v_readlane_b32 s39, v253, 15
	s_waitcnt lgkmcnt(0)
	v_add_f32_e32 v2, v1, v2
	ds_bpermute_b32 v1, v205, v142
	v_div_scale_f32 v3, s[22:23], v2, v2, 1.0
	v_rcp_f32_e32 v4, v3
	v_readlane_b32 s40, v253, 16
	s_waitcnt lgkmcnt(0)
	v_add_f32_e32 v1, v142, v1
	ds_bpermute_b32 v151, v141, v1
	v_fma_f32 v5, -v3, v4, 1.0
	v_fmac_f32_e32 v4, v5, v4
	v_div_scale_f32 v5, vcc, 1.0, v2, 1.0
	v_mul_f32_e32 v6, v5, v4
	v_fma_f32 v7, -v3, v6, v5
	v_fmac_f32_e32 v6, v7, v4
	v_fma_f32 v3, -v3, v6, v5
	s_waitcnt lgkmcnt(0)
	v_pk_add_f32 v[0:1], v[150:151], v[0:1]
	v_div_fmas_f32 v3, v3, v4, v6
	v_div_fixup_f32 v2, v3, v2, 1.0
	v_div_scale_f32 v3, s[22:23], v1, v1, v0
	v_rcp_f32_e32 v4, v3
	v_readlane_b32 s22, v251, 41
	v_readlane_b32 s41, v253, 17
	v_readlane_b32 s42, v253, 18
	v_fma_f32 v5, -v3, v4, 1.0
	v_fmac_f32_e32 v4, v5, v4
	v_div_scale_f32 v5, vcc, v0, v1, v0
	v_mul_f32_e32 v6, v5, v4
	v_fma_f32 v7, -v3, v6, v5
	v_fmac_f32_e32 v6, v7, v4
	v_fma_f32 v3, -v3, v6, v5
	v_div_fmas_f32 v3, v3, v4, v6
	v_div_fixup_f32 v0, v3, v1, v0
	v_or_b32_e32 v1, v206, v204
	v_mul_lo_u32 v1, v1, s52
	v_lshlrev_b32_e32 v3, 2, v209
	v_pk_mul_f32 v[4:5], v[76:77], v[0:1] op_sel_hi:[1,0]
	v_pk_mul_f32 v[8:9], v[78:79], v[0:1] op_sel_hi:[1,0]
	v_pk_fma_f32 v[4:5], v[108:109], v[2:3], v[4:5] op_sel_hi:[1,0,1] neg_lo:[0,0,1] neg_hi:[0,0,1]
	s_waitcnt vmcnt(1)
	v_add3_u32 v66, s17, v1, v3
	v_pk_mul_f32 v[6:7], v[4:5], v[4:5]
	v_pk_fma_f32 v[8:9], v[110:111], v[2:3], v[8:9] op_sel_hi:[1,0,1] neg_lo:[0,0,1] neg_hi:[0,0,1]
	v_pk_mul_f32 v[12:13], v[60:61], v[0:1] op_sel_hi:[1,0]
	v_pk_mul_f32 v[16:17], v[62:63], v[0:1] op_sel_hi:[1,0]
	v_pk_mul_f32 v[20:21], v[44:45], v[0:1] op_sel_hi:[1,0]
	v_pk_mul_f32 v[24:25], v[46:47], v[0:1] op_sel_hi:[1,0]
	v_pk_mul_f32 v[28:29], v[32:33], v[0:1] op_sel_hi:[1,0]
	v_pk_mul_f32 v[32:33], v[34:35], v[0:1] op_sel_hi:[1,0]
	v_pk_mul_f32 v[36:37], v[72:73], v[0:1] op_sel_hi:[1,0]
	v_pk_mul_f32 v[40:41], v[74:75], v[0:1] op_sel_hi:[1,0]
	v_pk_mul_f32 v[44:45], v[56:57], v[0:1] op_sel_hi:[1,0]
	v_pk_mul_f32 v[56:57], v[58:59], v[0:1] op_sel_hi:[1,0]
	v_pk_mul_f32 v[52:53], v[52:53], v[0:1] op_sel_hi:[1,0]
	v_pk_mul_f32 v[54:55], v[54:55], v[0:1] op_sel_hi:[1,0]
	v_pk_mul_f32 v[48:49], v[48:49], v[0:1] op_sel_hi:[1,0]
	v_pk_mul_f32 v[0:1], v[50:51], v[0:1] op_sel_hi:[1,0]
	v_pk_mul_f32 v[10:11], v[8:9], v[8:9]
	v_pk_fma_f32 v[12:13], v[104:105], v[2:3], v[12:13] op_sel_hi:[1,0,1] neg_lo:[0,0,1] neg_hi:[0,0,1]
	v_pk_fma_f32 v[16:17], v[106:107], v[2:3], v[16:17] op_sel_hi:[1,0,1] neg_lo:[0,0,1] neg_hi:[0,0,1]
	v_pk_fma_f32 v[20:21], v[100:101], v[2:3], v[20:21] op_sel_hi:[1,0,1] neg_lo:[0,0,1] neg_hi:[0,0,1]
	v_pk_fma_f32 v[24:25], v[102:103], v[2:3], v[24:25] op_sel_hi:[1,0,1] neg_lo:[0,0,1] neg_hi:[0,0,1]
	v_pk_fma_f32 v[28:29], v[92:93], v[2:3], v[28:29] op_sel_hi:[1,0,1] neg_lo:[0,0,1] neg_hi:[0,0,1]
	v_pk_fma_f32 v[32:33], v[94:95], v[2:3], v[32:33] op_sel_hi:[1,0,1] neg_lo:[0,0,1] neg_hi:[0,0,1]
	v_pk_fma_f32 v[36:37], v[96:97], v[2:3], v[36:37] op_sel_hi:[1,0,1] neg_lo:[0,0,1] neg_hi:[0,0,1]
	v_pk_fma_f32 v[40:41], v[98:99], v[2:3], v[40:41] op_sel_hi:[1,0,1] neg_lo:[0,0,1] neg_hi:[0,0,1]
	v_pk_fma_f32 v[44:45], v[88:89], v[2:3], v[44:45] op_sel_hi:[1,0,1] neg_lo:[0,0,1] neg_hi:[0,0,1]
	v_pk_fma_f32 v[56:57], v[90:91], v[2:3], v[56:57] op_sel_hi:[1,0,1] neg_lo:[0,0,1] neg_hi:[0,0,1]
	v_pk_fma_f32 v[52:53], v[84:85], v[2:3], v[52:53] op_sel_hi:[1,0,1] neg_lo:[0,0,1] neg_hi:[0,0,1]
	v_pk_fma_f32 v[54:55], v[86:87], v[2:3], v[54:55] op_sel_hi:[1,0,1] neg_lo:[0,0,1] neg_hi:[0,0,1]
	v_pk_fma_f32 v[48:49], v[80:81], v[2:3], v[48:49] op_sel_hi:[1,0,1] neg_lo:[0,0,1] neg_hi:[0,0,1]
	v_pk_fma_f32 v[50:51], v[82:83], v[2:3], v[0:1] op_sel_hi:[1,0,1] neg_lo:[0,0,1] neg_hi:[0,0,1]
	v_add_f32_e32 v2, v6, v7
	v_add_f32_e32 v2, v10, v2
	v_pk_mul_f32 v[14:15], v[12:13], v[12:13]
	v_add_f32_e32 v2, v11, v2
	v_add_f32_e32 v2, v14, v2
	v_pk_mul_f32 v[18:19], v[16:17], v[16:17]
	v_add_f32_e32 v2, v15, v2
	v_add_f32_e32 v2, v18, v2
	v_pk_mul_f32 v[22:23], v[20:21], v[20:21]
	v_add_f32_e32 v2, v19, v2
	v_add_f32_e32 v2, v22, v2
	v_pk_mul_f32 v[26:27], v[24:25], v[24:25]
	v_add_f32_e32 v2, v23, v2
	v_add_f32_e32 v2, v26, v2
	v_pk_mul_f32 v[30:31], v[28:29], v[28:29]
	v_add_f32_e32 v2, v27, v2
	v_add_f32_e32 v2, v30, v2
	v_pk_mul_f32 v[34:35], v[32:33], v[32:33]
	v_add_f32_e32 v2, v31, v2
	v_add_f32_e32 v2, v34, v2
	v_pk_mul_f32 v[38:39], v[36:37], v[36:37]
	v_add_f32_e32 v2, v35, v2
	v_add_f32_e32 v2, v38, v2
	v_pk_mul_f32 v[42:43], v[40:41], v[40:41]
	v_add_f32_e32 v2, v39, v2
	v_add_f32_e32 v2, v42, v2
	v_pk_mul_f32 v[46:47], v[44:45], v[44:45]
	v_add_f32_e32 v2, v43, v2
	v_add_f32_e32 v2, v46, v2
	v_pk_mul_f32 v[58:59], v[56:57], v[56:57]
	v_add_f32_e32 v2, v47, v2
	v_add_f32_e32 v2, v58, v2
	v_pk_mul_f32 v[60:61], v[52:53], v[52:53]
	v_add_f32_e32 v2, v59, v2
	v_add_f32_e32 v2, v60, v2
	v_pk_mul_f32 v[62:63], v[54:55], v[54:55]
	v_add_f32_e32 v2, v61, v2
	v_add_f32_e32 v2, v62, v2
	v_pk_mul_f32 v[64:65], v[48:49], v[48:49]
	v_add_f32_e32 v2, v63, v2
	v_add_f32_e32 v2, v64, v2
	v_pk_mul_f32 v[0:1], v[50:51], v[50:51]
	v_add_f32_e32 v2, v65, v2
	v_add_f32_e32 v0, v0, v2
	v_add_f32_e32 v0, v1, v0
	ds_bpermute_b32 v1, v205, v0
	v_mov_b64_e32 v[14:15], s[6:7]
	v_readlane_b32 s43, v253, 19
	v_readlane_b32 s44, v253, 20
	v_readlane_b32 s45, v253, 21
	s_waitcnt lgkmcnt(0)
	v_add_f32_e32 v0, v0, v1
	ds_bpermute_b32 v1, v141, v0
	v_readlane_b32 s46, v253, 22
	v_readlane_b32 s47, v253, 23
	v_readlane_b32 s50, v253, 26
	v_readlane_b32 s51, v253, 27
	s_waitcnt lgkmcnt(0)
	v_add_f32_e32 v0, v0, v1
	v_fmamk_f32 v0, v0, 0x3c000000, v193
	v_cmp_gt_f32_e32 vcc, s79, v0
	v_mul_f32_e32 v1, 0x4b800000, v0
	s_nop 0
	v_cndmask_b32_e32 v0, v0, v1, vcc
	v_rsq_f32_e32 v0, v0
	s_nop 0
	v_mul_f32_e32 v1, 0x45800000, v0
	v_cndmask_b32_e32 v0, v0, v1, vcc
	v_mul_f32_e32 v6, v203, v0
	v_pk_mul_f32 v[0:1], v[4:5], v[6:7] op_sel_hi:[1,0]
	v_pk_mul_f32 v[2:3], v[8:9], v[6:7] op_sel_hi:[1,0]
	ds_write_b128 v66, v[0:3]
	v_pk_mul_f32 v[0:1], v[12:13], v[6:7] op_sel_hi:[1,0]
	v_pk_mul_f32 v[2:3], v[16:17], v[6:7] op_sel_hi:[1,0]
	ds_write_b128 v66, v[0:3] offset:64
	v_pk_mul_f32 v[0:1], v[20:21], v[6:7] op_sel_hi:[1,0]
	v_pk_mul_f32 v[2:3], v[24:25], v[6:7] op_sel_hi:[1,0]
	ds_write_b128 v66, v[0:3] offset:128
	v_pk_mul_f32 v[0:1], v[28:29], v[6:7] op_sel_hi:[1,0]
	v_pk_mul_f32 v[2:3], v[32:33], v[6:7] op_sel_hi:[1,0]
	ds_write_b128 v66, v[0:3] offset:192
	v_pk_mul_f32 v[0:1], v[36:37], v[6:7] op_sel_hi:[1,0]
	v_pk_mul_f32 v[2:3], v[40:41], v[6:7] op_sel_hi:[1,0]
	ds_write_b128 v66, v[0:3] offset:256
	v_pk_mul_f32 v[0:1], v[44:45], v[6:7] op_sel_hi:[1,0]
	v_pk_mul_f32 v[2:3], v[56:57], v[6:7] op_sel_hi:[1,0]
	ds_write_b128 v66, v[0:3] offset:320
	v_pk_mul_f32 v[0:1], v[52:53], v[6:7] op_sel_hi:[1,0]
	v_pk_mul_f32 v[2:3], v[54:55], v[6:7] op_sel_hi:[1,0]
	ds_write_b128 v66, v[0:3] offset:384
	v_pk_mul_f32 v[0:1], v[48:49], v[6:7] op_sel_hi:[1,0]
	v_pk_mul_f32 v[2:3], v[50:51], v[6:7] op_sel_hi:[1,0]
	v_and_b32_e32 v5, 0x78, v207
	v_add_u32_e32 v16, s20, v138
	ds_write_b128 v66, v[0:3] offset:448
	v_or_b32_e32 v4, s22, v5
	v_mad_i64_i32 v[0:1], s[22:23], v16, s0, v[14:15]
	v_lshl_add_u64 v[0:1], v[0:1], 0, s[70:71]
	v_lshlrev_b32_e32 v160, 1, v5
	v_lshl_add_u64 v[0:1], v[0:1], 0, v[160:161]
	v_add_co_u32_e32 v0, vcc, s3, v0
	s_waitcnt lgkmcnt(0)
	s_nop 0
	v_addc_co_u32_e32 v1, vcc, 0, v1, vcc
	s_barrier
	global_load_dwordx4 v[0:3], v[0:1], off
	v_mul_lo_u32 v6, v138, s52
	v_lshlrev_b32_e32 v20, 2, v5
	v_mov_b32_e32 v5, v161
	v_add3_u32 v6, s17, v6, v20
	v_lshl_add_u64 v[12:13], v[4:5], 2, s[48:49]
	v_ashrrev_i32_e32 v17, 31, v16
	s_waitcnt vmcnt(1)
	global_load_dwordx4 v[8:11], v[12:13], off offset:16
	global_load_dwordx4 v[26:29], v[12:13], off
	v_add_u32_e32 v64, s20, v136
	v_mad_i64_i32 v[68:69], s[100:101], v64, s0, v[14:15]
	v_lshl_add_u64 v[70:71], v[68:69], 0, s[70:71]
	v_lshl_add_u64 v[72:73], v[70:71], 0, v[160:161]
	v_add_co_u32_e32 v72, vcc, s3, v72
	s_nop 1
	v_addc_co_u32_e32 v73, vcc, 0, v73, vcc
	global_load_dwordx4 v[74:77], v[72:73], off
	global_load_dwordx4 v[68:71], v[12:13], off offset:16
	global_load_dwordx4 v[78:81], v[12:13], off
	v_add_u32_e32 v72, s20, v134
	v_mad_i64_i32 v[84:85], s[100:101], v72, s0, v[14:15]
	v_lshl_add_u64 v[86:87], v[84:85], 0, s[70:71]
	v_lshl_add_u64 v[88:89], v[86:87], 0, v[160:161]
	v_add_co_u32_e32 v88, vcc, s3, v88
	s_nop 1
	v_addc_co_u32_e32 v89, vcc, 0, v89, vcc
	global_load_dwordx4 v[90:93], v[88:89], off
	global_load_dwordx4 v[84:87], v[12:13], off offset:16
	global_load_dwordx4 v[110:113], v[12:13], off
	v_add_u32_e32 v88, s20, v132
	v_mad_i64_i32 v[116:117], s[100:101], v88, s0, v[14:15]
	v_lshl_add_u64 v[118:119], v[116:117], 0, s[70:71]
	v_lshl_add_u64 v[120:121], v[118:119], 0, v[160:161]
	v_add_co_u32_e32 v120, vcc, s3, v120
	s_nop 1
	v_addc_co_u32_e32 v121, vcc, 0, v121, vcc
	global_load_dwordx4 v[122:125], v[120:121], off
	global_load_dwordx4 v[116:119], v[12:13], off offset:16
	global_load_dwordx4 v[12:15], v[12:13], off
	s_waitcnt vmcnt(11)
	v_and_b32_e32 v21, 0xffff0000, v0
	v_lshlrev_b32_e32 v0, 16, v0
	v_mul_f32_e32 v4, 0xbfb8aa3b, v0
	v_exp_f32_e32 v18, v4
	ds_read_b128 v[22:25], v6
	ds_read_b128 v[4:7], v6 offset:16
	s_nop 0
	s_nop 0
	v_mul_f32_e32 v19, 0xbfb8aa3b, v21
	v_exp_f32_e32 v19, v19
	s_waitcnt  lgkmcnt(0)
	s_waitcnt vmcnt(10)
	v_pk_mul_f32 v[4:5], v[4:5], v[8:9]
	v_pk_add_f32 v[18:19], v[18:19], 1.0 op_sel_hi:[1,0]
	s_waitcnt vmcnt(9)
	v_pk_mul_f32 v[22:23], v[22:23], v[26:27]
	v_div_scale_f32 v26, s[22:23], v19, v19, v21
	v_rcp_f32_e32 v27, v26
	v_pk_mul_f32 v[6:7], v[6:7], v[10:11]
	v_fma_f32 v30, -v26, v27, 1.0
	v_fmac_f32_e32 v27, v30, v27
	v_div_scale_f32 v30, vcc, v21, v19, v21
	v_mul_f32_e32 v31, v30, v27
	v_fma_f32 v32, -v26, v31, v30
	v_fmac_f32_e32 v31, v32, v27
	v_fma_f32 v26, -v26, v31, v30
	v_div_fmas_f32 v26, v26, v27, v31
	v_div_fixup_f32 v19, v26, v19, v21
	v_div_scale_f32 v21, s[22:23], v18, v18, v0
	v_rcp_f32_e32 v26, v21
	s_nop 0
	v_fma_f32 v27, -v21, v26, 1.0
	v_fmac_f32_e32 v26, v27, v26
	v_div_scale_f32 v27, vcc, v0, v18, v0
	v_mul_f32_e32 v30, v27, v26
	v_fma_f32 v31, -v21, v30, v27
	v_fmac_f32_e32 v30, v31, v26
	v_fma_f32 v21, -v21, v30, v27
	v_div_fmas_f32 v21, v21, v26, v30
	v_div_fixup_f32 v18, v21, v18, v0
	v_and_b32_e32 v21, 0xffff0000, v1
	v_lshlrev_b32_e32 v26, 16, v1
	v_mul_f32_e32 v0, 0xbfb8aa3b, v26
	v_mul_f32_e32 v1, 0xbfb8aa3b, v21
	v_exp_f32_e32 v0, v0
	v_exp_f32_e32 v1, v1
	v_pk_mul_f32 v[18:19], v[22:23], v[18:19]
	v_pk_mul_f32 v[22:23], v[24:25], v[28:29]
	v_pk_add_f32 v[0:1], v[0:1], 1.0 op_sel_hi:[1,0]
	s_nop 0
	v_div_scale_f32 v24, s[22:23], v1, v1, v21
	v_rcp_f32_e32 v25, v24
	s_nop 0
	v_fma_f32 v27, -v24, v25, 1.0
	v_fmac_f32_e32 v25, v27, v25
	v_div_scale_f32 v27, vcc, v21, v1, v21
	v_mul_f32_e32 v28, v27, v25
	v_fma_f32 v29, -v24, v28, v27
	v_fmac_f32_e32 v28, v29, v25
	v_fma_f32 v24, -v24, v28, v27
	v_div_fmas_f32 v24, v24, v25, v28
	v_div_fixup_f32 v1, v24, v1, v21
	v_div_scale_f32 v21, s[22:23], v0, v0, v26
	v_rcp_f32_e32 v24, v21
	s_nop 0
	v_fma_f32 v25, -v21, v24, 1.0
	v_fmac_f32_e32 v24, v25, v24
	v_div_scale_f32 v25, vcc, v26, v0, v26
	v_mul_f32_e32 v27, v25, v24
	v_fma_f32 v28, -v21, v27, v25
	v_fmac_f32_e32 v27, v28, v24
	v_fma_f32 v21, -v21, v27, v25
	v_div_fmas_f32 v21, v21, v24, v27
	v_div_fixup_f32 v0, v21, v0, v26
	v_and_b32_e32 v21, 0xffff0000, v2
	v_lshlrev_b32_e32 v2, 16, v2
	v_pk_mul_f32 v[0:1], v[22:23], v[0:1]
	v_mul_f32_e32 v22, 0xbfb8aa3b, v2
	v_mul_f32_e32 v8, 0xbfb8aa3b, v21
	v_exp_f32_e32 v22, v22
	v_exp_f32_e32 v23, v8
	s_nop 0
	v_pk_add_f32 v[8:9], v[22:23], 1.0 op_sel_hi:[1,0]
	s_nop 0
	v_div_scale_f32 v22, s[22:23], v9, v9, v21
	v_rcp_f32_e32 v23, v22
	s_nop 0
	v_fma_f32 v24, -v22, v23, 1.0
	v_fmac_f32_e32 v23, v24, v23
	v_div_scale_f32 v24, vcc, v21, v9, v21
	v_mul_f32_e32 v25, v24, v23
	v_fma_f32 v26, -v22, v25, v24
	v_fmac_f32_e32 v25, v26, v23
	v_fma_f32 v22, -v22, v25, v24
	v_div_fmas_f32 v22, v22, v23, v25
	v_div_fixup_f32 v9, v22, v9, v21
	v_div_scale_f32 v21, s[22:23], v8, v8, v2
	v_rcp_f32_e32 v22, v21
	s_nop 0
	v_fma_f32 v23, -v21, v22, 1.0
	v_fmac_f32_e32 v22, v23, v22
	v_div_scale_f32 v23, vcc, v2, v8, v2
	v_mul_f32_e32 v24, v23, v22
	v_fma_f32 v25, -v21, v24, v23
	v_fmac_f32_e32 v24, v25, v22
	v_fma_f32 v21, -v21, v24, v23
	v_div_fmas_f32 v21, v21, v22, v24
	v_div_fixup_f32 v8, v21, v8, v2
	v_pk_mul_f32 v[4:5], v[8:9], v[4:5]
	v_and_b32_e32 v8, 0xffff0000, v3
	v_lshlrev_b32_e32 v9, 16, v3
	v_mul_f32_e32 v2, 0xbfb8aa3b, v9
	v_mul_f32_e32 v3, 0xbfb8aa3b, v8
	v_exp_f32_e32 v2, v2
	v_exp_f32_e32 v3, v3
	s_nop 0
	v_pk_add_f32 v[2:3], v[2:3], 1.0 op_sel_hi:[1,0]
	s_nop 0
	v_div_scale_f32 v10, s[22:23], v3, v3, v8
	v_rcp_f32_e32 v11, v10
	s_nop 0
	v_fma_f32 v21, -v10, v11, 1.0
	v_fmac_f32_e32 v11, v21, v11
	v_div_scale_f32 v21, vcc, v8, v3, v8
	v_mul_f32_e32 v22, v21, v11
	v_fma_f32 v23, -v10, v22, v21
	v_fmac_f32_e32 v22, v23, v11
	v_fma_f32 v10, -v10, v22, v21
	v_div_fmas_f32 v10, v10, v11, v22
	v_div_fixup_f32 v3, v10, v3, v8
	v_div_scale_f32 v8, s[22:23], v2, v2, v9
	v_rcp_f32_e32 v10, v8
	s_nop 0
	v_fma_f32 v11, -v8, v10, 1.0
	v_fmac_f32_e32 v10, v11, v10
	v_div_scale_f32 v11, vcc, v9, v2, v9
	v_mul_f32_e32 v21, v11, v10
	v_fma_f32 v22, -v8, v21, v11
	v_fmac_f32_e32 v21, v22, v10
	v_fma_f32 v8, -v8, v21, v11
	v_div_fmas_f32 v8, v8, v10, v21
	v_div_fixup_f32 v2, v8, v2, v9
	v_pk_mul_f32 v[2:3], v[2:3], v[6:7]
	v_cvt_pk_bf16_f32 v4, v4, v5
	v_cvt_pk_bf16_f32 v2, v2, v3
	v_mov_b32_e32 v3, v2
	v_mov_b32_e32 v2, v4
	v_lshlrev_b64 v[4:5], 12, v[16:17]
	v_lshl_add_u64 v[4:5], s[30:31], 0, v[4:5]
	v_lshl_add_u64 v[4:5], v[4:5], 0, s[70:71]
	v_lshl_add_u64 v[4:5], v[4:5], 0, v[160:161]
	v_cvt_pk_bf16_f32 v18, v18, v19
	v_cvt_pk_bf16_f32 v0, v0, v1
	v_add_co_u32_e32 v4, vcc, s21, v4
	v_mov_b32_e32 v1, v0
	v_mov_b32_e32 v0, v18
	v_addc_co_u32_e32 v5, vcc, 0, v5, vcc
	v_add_u32_e32 v16, s20, v136
	global_store_dwordx4 v[4:5], v[0:3], off offset:2048
	v_mul_lo_u32 v4, v136, s52
	v_add3_u32 v4, s17, v4, v20
	s_nop 0
	s_nop 0
	s_nop 0
	s_nop 0
	v_ashrrev_i32_e32 v17, 31, v16
	s_nop 0
	s_nop 0
	s_nop 0
	s_waitcnt vmcnt(9)
	v_and_b32_e32 v21, 0xffff0000, v74
	v_lshlrev_b32_e32 v0, 16, v74
	v_mul_f32_e32 v5, 0xbfb8aa3b, v0
	v_exp_f32_e32 v18, v5
	ds_read_b128 v[22:25], v4
	ds_read_b128 v[4:7], v4 offset:16
	s_nop 0
	s_nop 0
	v_mul_f32_e32 v19, 0xbfb8aa3b, v21
	v_exp_f32_e32 v19, v19
	s_waitcnt  lgkmcnt(0)
	s_waitcnt vmcnt(8)
	v_pk_mul_f32 v[4:5], v[4:5], v[68:69]
	v_pk_add_f32 v[18:19], v[18:19], 1.0 op_sel_hi:[1,0]
	s_waitcnt vmcnt(7)
	v_pk_mul_f32 v[22:23], v[22:23], v[78:79]
	v_div_scale_f32 v26, s[22:23], v19, v19, v21
	v_rcp_f32_e32 v27, v26
	v_pk_mul_f32 v[6:7], v[6:7], v[70:71]
	v_fma_f32 v30, -v26, v27, 1.0
	v_fmac_f32_e32 v27, v30, v27
	v_div_scale_f32 v30, vcc, v21, v19, v21
	v_mul_f32_e32 v31, v30, v27
	v_fma_f32 v32, -v26, v31, v30
	v_fmac_f32_e32 v31, v32, v27
	v_fma_f32 v26, -v26, v31, v30
	v_div_fmas_f32 v26, v26, v27, v31
	v_div_fixup_f32 v19, v26, v19, v21
	v_div_scale_f32 v21, s[22:23], v18, v18, v0
	v_rcp_f32_e32 v26, v21
	s_nop 0
	v_fma_f32 v27, -v21, v26, 1.0
	v_fmac_f32_e32 v26, v27, v26
	v_div_scale_f32 v27, vcc, v0, v18, v0
	v_mul_f32_e32 v30, v27, v26
	v_fma_f32 v31, -v21, v30, v27
	v_fmac_f32_e32 v30, v31, v26
	v_fma_f32 v21, -v21, v30, v27
	v_div_fmas_f32 v21, v21, v26, v30
	v_div_fixup_f32 v18, v21, v18, v0
	v_and_b32_e32 v21, 0xffff0000, v75
	v_lshlrev_b32_e32 v26, 16, v75
	v_mul_f32_e32 v0, 0xbfb8aa3b, v26
	v_mul_f32_e32 v1, 0xbfb8aa3b, v21
	v_exp_f32_e32 v0, v0
	v_exp_f32_e32 v1, v1
	v_pk_mul_f32 v[18:19], v[22:23], v[18:19]
	v_pk_mul_f32 v[22:23], v[24:25], v[80:81]
	v_pk_add_f32 v[0:1], v[0:1], 1.0 op_sel_hi:[1,0]
	s_nop 0
	v_div_scale_f32 v24, s[22:23], v1, v1, v21
	v_rcp_f32_e32 v25, v24
	s_nop 0
	v_fma_f32 v27, -v24, v25, 1.0
	v_fmac_f32_e32 v25, v27, v25
	v_div_scale_f32 v27, vcc, v21, v1, v21
	v_mul_f32_e32 v28, v27, v25
	v_fma_f32 v29, -v24, v28, v27
	v_fmac_f32_e32 v28, v29, v25
	v_fma_f32 v24, -v24, v28, v27
	v_div_fmas_f32 v24, v24, v25, v28
	v_div_fixup_f32 v1, v24, v1, v21
	v_div_scale_f32 v21, s[22:23], v0, v0, v26
	v_rcp_f32_e32 v24, v21
	s_nop 0
	v_fma_f32 v25, -v21, v24, 1.0
	v_fmac_f32_e32 v24, v25, v24
	v_div_scale_f32 v25, vcc, v26, v0, v26
	v_mul_f32_e32 v27, v25, v24
	v_fma_f32 v28, -v21, v27, v25
	v_fmac_f32_e32 v27, v28, v24
	v_fma_f32 v21, -v21, v27, v25
	v_div_fmas_f32 v21, v21, v24, v27
	v_div_fixup_f32 v0, v21, v0, v26
	v_and_b32_e32 v21, 0xffff0000, v76
	v_lshlrev_b32_e32 v2, 16, v76
	v_pk_mul_f32 v[0:1], v[22:23], v[0:1]
	v_mul_f32_e32 v22, 0xbfb8aa3b, v2
	v_mul_f32_e32 v8, 0xbfb8aa3b, v21
	v_exp_f32_e32 v22, v22
	v_exp_f32_e32 v23, v8
	s_nop 0
	v_pk_add_f32 v[8:9], v[22:23], 1.0 op_sel_hi:[1,0]
	s_nop 0
	v_div_scale_f32 v22, s[22:23], v9, v9, v21
	v_rcp_f32_e32 v23, v22
	s_nop 0
	v_fma_f32 v24, -v22, v23, 1.0
	v_fmac_f32_e32 v23, v24, v23
	v_div_scale_f32 v24, vcc, v21, v9, v21
	v_mul_f32_e32 v25, v24, v23
	v_fma_f32 v26, -v22, v25, v24
	v_fmac_f32_e32 v25, v26, v23
	v_fma_f32 v22, -v22, v25, v24
	v_div_fmas_f32 v22, v22, v23, v25
	v_div_fixup_f32 v9, v22, v9, v21
	v_div_scale_f32 v21, s[22:23], v8, v8, v2
	v_rcp_f32_e32 v22, v21
	s_nop 0
	v_fma_f32 v23, -v21, v22, 1.0
	v_fmac_f32_e32 v22, v23, v22
	v_div_scale_f32 v23, vcc, v2, v8, v2
	v_mul_f32_e32 v24, v23, v22
	v_fma_f32 v25, -v21, v24, v23
	v_fmac_f32_e32 v24, v25, v22
	v_fma_f32 v21, -v21, v24, v23
	v_div_fmas_f32 v21, v21, v22, v24
	v_div_fixup_f32 v8, v21, v8, v2
	v_pk_mul_f32 v[4:5], v[8:9], v[4:5]
	v_and_b32_e32 v8, 0xffff0000, v77
	v_lshlrev_b32_e32 v9, 16, v77
	v_mul_f32_e32 v2, 0xbfb8aa3b, v9
	v_mul_f32_e32 v3, 0xbfb8aa3b, v8
	v_exp_f32_e32 v2, v2
	v_exp_f32_e32 v3, v3
	s_nop 0
	v_pk_add_f32 v[2:3], v[2:3], 1.0 op_sel_hi:[1,0]
	s_nop 0
	v_div_scale_f32 v10, s[22:23], v3, v3, v8
	v_rcp_f32_e32 v11, v10
	s_nop 0
	v_fma_f32 v21, -v10, v11, 1.0
	v_fmac_f32_e32 v11, v21, v11
	v_div_scale_f32 v21, vcc, v8, v3, v8
	v_mul_f32_e32 v22, v21, v11
	v_fma_f32 v23, -v10, v22, v21
	v_fmac_f32_e32 v22, v23, v11
	v_fma_f32 v10, -v10, v22, v21
	v_div_fmas_f32 v10, v10, v11, v22
	v_div_fixup_f32 v3, v10, v3, v8
	v_div_scale_f32 v8, s[22:23], v2, v2, v9
	v_rcp_f32_e32 v10, v8
	s_nop 0
	v_fma_f32 v11, -v8, v10, 1.0
	v_fmac_f32_e32 v10, v11, v10
	v_div_scale_f32 v11, vcc, v9, v2, v9
	v_mul_f32_e32 v21, v11, v10
	v_fma_f32 v22, -v8, v21, v11
	v_fmac_f32_e32 v21, v22, v10
	v_fma_f32 v8, -v8, v21, v11
	v_div_fmas_f32 v8, v8, v10, v21
	v_div_fixup_f32 v2, v8, v2, v9
	v_pk_mul_f32 v[2:3], v[2:3], v[6:7]
	v_cvt_pk_bf16_f32 v4, v4, v5
	v_cvt_pk_bf16_f32 v2, v2, v3
	v_mov_b32_e32 v3, v2
	v_mov_b32_e32 v2, v4
	v_lshlrev_b64 v[4:5], 12, v[16:17]
	v_lshl_add_u64 v[4:5], s[30:31], 0, v[4:5]
	v_lshl_add_u64 v[4:5], v[4:5], 0, s[70:71]
	v_lshl_add_u64 v[4:5], v[4:5], 0, v[160:161]
	v_cvt_pk_bf16_f32 v18, v18, v19
	v_cvt_pk_bf16_f32 v0, v0, v1
	v_add_co_u32_e32 v4, vcc, s21, v4
	v_mov_b32_e32 v1, v0
	v_mov_b32_e32 v0, v18
	v_addc_co_u32_e32 v5, vcc, 0, v5, vcc
	v_add_u32_e32 v16, s20, v134
	global_store_dwordx4 v[4:5], v[0:3], off offset:2048
	v_mul_lo_u32 v4, v134, s52
	v_add3_u32 v4, s17, v4, v20
	s_nop 0
	s_nop 0
	s_nop 0
	s_nop 0
	v_ashrrev_i32_e32 v17, 31, v16
	s_nop 0
	s_nop 0
	s_nop 0
	s_waitcnt vmcnt(7)
	v_and_b32_e32 v21, 0xffff0000, v90
	v_lshlrev_b32_e32 v0, 16, v90
	v_mul_f32_e32 v5, 0xbfb8aa3b, v0
	v_exp_f32_e32 v18, v5
	ds_read_b128 v[22:25], v4
	ds_read_b128 v[4:7], v4 offset:16
	s_nop 0
	s_nop 0
	v_mul_f32_e32 v19, 0xbfb8aa3b, v21
	v_exp_f32_e32 v19, v19
	s_waitcnt  lgkmcnt(0)
	s_waitcnt vmcnt(6)
	v_pk_mul_f32 v[4:5], v[4:5], v[84:85]
	v_pk_add_f32 v[18:19], v[18:19], 1.0 op_sel_hi:[1,0]
	s_waitcnt vmcnt(5)
	v_pk_mul_f32 v[22:23], v[22:23], v[110:111]
	v_div_scale_f32 v26, s[22:23], v19, v19, v21
	v_rcp_f32_e32 v27, v26
	v_pk_mul_f32 v[6:7], v[6:7], v[86:87]
	v_fma_f32 v30, -v26, v27, 1.0
	v_fmac_f32_e32 v27, v30, v27
	v_div_scale_f32 v30, vcc, v21, v19, v21
	v_mul_f32_e32 v31, v30, v27
	v_fma_f32 v32, -v26, v31, v30
	v_fmac_f32_e32 v31, v32, v27
	v_fma_f32 v26, -v26, v31, v30
	v_div_fmas_f32 v26, v26, v27, v31
	v_div_fixup_f32 v19, v26, v19, v21
	v_div_scale_f32 v21, s[22:23], v18, v18, v0
	v_rcp_f32_e32 v26, v21
	s_nop 0
	v_fma_f32 v27, -v21, v26, 1.0
	v_fmac_f32_e32 v26, v27, v26
	v_div_scale_f32 v27, vcc, v0, v18, v0
	v_mul_f32_e32 v30, v27, v26
	v_fma_f32 v31, -v21, v30, v27
	v_fmac_f32_e32 v30, v31, v26
	v_fma_f32 v21, -v21, v30, v27
	v_div_fmas_f32 v21, v21, v26, v30
	v_div_fixup_f32 v18, v21, v18, v0
	v_and_b32_e32 v21, 0xffff0000, v91
	v_lshlrev_b32_e32 v26, 16, v91
	v_mul_f32_e32 v0, 0xbfb8aa3b, v26
	v_mul_f32_e32 v1, 0xbfb8aa3b, v21
	v_exp_f32_e32 v0, v0
	v_exp_f32_e32 v1, v1
	v_pk_mul_f32 v[18:19], v[22:23], v[18:19]
	v_pk_mul_f32 v[22:23], v[24:25], v[112:113]
	v_pk_add_f32 v[0:1], v[0:1], 1.0 op_sel_hi:[1,0]
	s_nop 0
	v_div_scale_f32 v24, s[22:23], v1, v1, v21
	v_rcp_f32_e32 v25, v24
	s_nop 0
	v_fma_f32 v27, -v24, v25, 1.0
	v_fmac_f32_e32 v25, v27, v25
	v_div_scale_f32 v27, vcc, v21, v1, v21
	v_mul_f32_e32 v28, v27, v25
	v_fma_f32 v29, -v24, v28, v27
	v_fmac_f32_e32 v28, v29, v25
	v_fma_f32 v24, -v24, v28, v27
	v_div_fmas_f32 v24, v24, v25, v28
	v_div_fixup_f32 v1, v24, v1, v21
	v_div_scale_f32 v21, s[22:23], v0, v0, v26
	v_rcp_f32_e32 v24, v21
	s_nop 0
	v_fma_f32 v25, -v21, v24, 1.0
	v_fmac_f32_e32 v24, v25, v24
	v_div_scale_f32 v25, vcc, v26, v0, v26
	v_mul_f32_e32 v27, v25, v24
	v_fma_f32 v28, -v21, v27, v25
	v_fmac_f32_e32 v27, v28, v24
	v_fma_f32 v21, -v21, v27, v25
	v_div_fmas_f32 v21, v21, v24, v27
	v_div_fixup_f32 v0, v21, v0, v26
	v_and_b32_e32 v21, 0xffff0000, v92
	v_lshlrev_b32_e32 v2, 16, v92
	v_pk_mul_f32 v[0:1], v[22:23], v[0:1]
	v_mul_f32_e32 v22, 0xbfb8aa3b, v2
	v_mul_f32_e32 v8, 0xbfb8aa3b, v21
	v_exp_f32_e32 v22, v22
	v_exp_f32_e32 v23, v8
	s_nop 0
	v_pk_add_f32 v[8:9], v[22:23], 1.0 op_sel_hi:[1,0]
	s_nop 0
	v_div_scale_f32 v22, s[22:23], v9, v9, v21
	v_rcp_f32_e32 v23, v22
	s_nop 0
	v_fma_f32 v24, -v22, v23, 1.0
	v_fmac_f32_e32 v23, v24, v23
	v_div_scale_f32 v24, vcc, v21, v9, v21
	v_mul_f32_e32 v25, v24, v23
	v_fma_f32 v26, -v22, v25, v24
	v_fmac_f32_e32 v25, v26, v23
	v_fma_f32 v22, -v22, v25, v24
	v_div_fmas_f32 v22, v22, v23, v25
	v_div_fixup_f32 v9, v22, v9, v21
	v_div_scale_f32 v21, s[22:23], v8, v8, v2
	v_rcp_f32_e32 v22, v21
	s_nop 0
	v_fma_f32 v23, -v21, v22, 1.0
	v_fmac_f32_e32 v22, v23, v22
	v_div_scale_f32 v23, vcc, v2, v8, v2
	v_mul_f32_e32 v24, v23, v22
	v_fma_f32 v25, -v21, v24, v23
	v_fmac_f32_e32 v24, v25, v22
	v_fma_f32 v21, -v21, v24, v23
	v_div_fmas_f32 v21, v21, v22, v24
	v_div_fixup_f32 v8, v21, v8, v2
	v_pk_mul_f32 v[4:5], v[8:9], v[4:5]
	v_and_b32_e32 v8, 0xffff0000, v93
	v_lshlrev_b32_e32 v9, 16, v93
	v_mul_f32_e32 v2, 0xbfb8aa3b, v9
	v_mul_f32_e32 v3, 0xbfb8aa3b, v8
	v_exp_f32_e32 v2, v2
	v_exp_f32_e32 v3, v3
	s_nop 0
	v_pk_add_f32 v[2:3], v[2:3], 1.0 op_sel_hi:[1,0]
	s_nop 0
	v_div_scale_f32 v10, s[22:23], v3, v3, v8
	v_rcp_f32_e32 v11, v10
	s_nop 0
	v_fma_f32 v21, -v10, v11, 1.0
	v_fmac_f32_e32 v11, v21, v11
	v_div_scale_f32 v21, vcc, v8, v3, v8
	v_mul_f32_e32 v22, v21, v11
	v_fma_f32 v23, -v10, v22, v21
	v_fmac_f32_e32 v22, v23, v11
	v_fma_f32 v10, -v10, v22, v21
	v_div_fmas_f32 v10, v10, v11, v22
	v_div_fixup_f32 v3, v10, v3, v8
	v_div_scale_f32 v8, s[22:23], v2, v2, v9
	v_rcp_f32_e32 v10, v8
	s_nop 0
	v_fma_f32 v11, -v8, v10, 1.0
	v_fmac_f32_e32 v10, v11, v10
	v_div_scale_f32 v11, vcc, v9, v2, v9
	v_mul_f32_e32 v21, v11, v10
	v_fma_f32 v22, -v8, v21, v11
	v_fmac_f32_e32 v21, v22, v10
	v_fma_f32 v8, -v8, v21, v11
	v_div_fmas_f32 v8, v8, v10, v21
	v_div_fixup_f32 v2, v8, v2, v9
	v_pk_mul_f32 v[2:3], v[2:3], v[6:7]
	v_cvt_pk_bf16_f32 v4, v4, v5
	v_cvt_pk_bf16_f32 v2, v2, v3
	v_mov_b32_e32 v3, v2
	v_mov_b32_e32 v2, v4
	v_lshlrev_b64 v[4:5], 12, v[16:17]
	v_lshl_add_u64 v[4:5], s[30:31], 0, v[4:5]
	v_lshl_add_u64 v[4:5], v[4:5], 0, s[70:71]
	v_lshl_add_u64 v[4:5], v[4:5], 0, v[160:161]
	v_cvt_pk_bf16_f32 v18, v18, v19
	v_cvt_pk_bf16_f32 v0, v0, v1
	v_add_co_u32_e32 v4, vcc, s21, v4
	v_mov_b32_e32 v1, v0
	v_mov_b32_e32 v0, v18
	v_addc_co_u32_e32 v5, vcc, 0, v5, vcc
	v_add_u32_e32 v16, s20, v132
	global_store_dwordx4 v[4:5], v[0:3], off offset:2048
	v_mul_lo_u32 v4, v132, s52
	v_add3_u32 v4, s17, v4, v20
	s_nop 0
	s_nop 0
	s_nop 0
	s_nop 0
	v_ashrrev_i32_e32 v17, 31, v16
	s_nop 0
	s_nop 0
	s_nop 0
	s_waitcnt vmcnt(5)
	v_and_b32_e32 v24, 0xffff0000, v122
	v_lshlrev_b32_e32 v0, 16, v122
	v_mul_f32_e32 v5, 0xbfb8aa3b, v0
	v_exp_f32_e32 v22, v5
	ds_read_b128 v[18:21], v4
	ds_read_b128 v[4:7], v4 offset:16
	s_nop 0
	s_nop 0
	s_nop 0
	s_waitcnt  lgkmcnt(0)
	s_waitcnt vmcnt(4)
	v_pk_mul_f32 v[4:5], v[4:5], v[116:117]
	s_waitcnt vmcnt(3)
	v_pk_mul_f32 v[12:13], v[18:19], v[12:13]
	v_mul_f32_e32 v18, 0xbfb8aa3b, v24
	v_exp_f32_e32 v23, v18
	v_pk_mul_f32 v[14:15], v[20:21], v[14:15]
	v_pk_mul_f32 v[6:7], v[6:7], v[118:119]
	v_pk_add_f32 v[18:19], v[22:23], 1.0 op_sel_hi:[1,0]
	s_nop 0
	v_div_scale_f32 v22, s[20:21], v19, v19, v24
	v_rcp_f32_e32 v23, v22
	s_nop 0
	v_fma_f32 v25, -v22, v23, 1.0
	v_fmac_f32_e32 v23, v25, v23
	v_div_scale_f32 v25, vcc, v24, v19, v24
	v_mul_f32_e32 v26, v25, v23
	v_fma_f32 v27, -v22, v26, v25
	v_fmac_f32_e32 v26, v27, v23
	v_fma_f32 v22, -v22, v26, v25
	v_div_fmas_f32 v22, v22, v23, v26
	v_div_fixup_f32 v19, v22, v19, v24
	v_div_scale_f32 v22, s[20:21], v18, v18, v0
	v_rcp_f32_e32 v23, v22
	s_nop 0
	v_fma_f32 v24, -v22, v23, 1.0
	v_fmac_f32_e32 v23, v24, v23
	v_div_scale_f32 v24, vcc, v0, v18, v0
	v_mul_f32_e32 v25, v24, v23
	v_fma_f32 v26, -v22, v25, v24
	v_fmac_f32_e32 v25, v26, v23
	v_fma_f32 v22, -v22, v25, v24
	v_div_fmas_f32 v22, v22, v23, v25
	v_div_fixup_f32 v18, v22, v18, v0
	v_pk_mul_f32 v[12:13], v[12:13], v[18:19]
	v_and_b32_e32 v18, 0xffff0000, v123
	v_lshlrev_b32_e32 v19, 16, v123
	v_mul_f32_e32 v0, 0xbfb8aa3b, v19
	v_mul_f32_e32 v1, 0xbfb8aa3b, v18
	v_exp_f32_e32 v0, v0
	v_exp_f32_e32 v1, v1
	s_nop 0
	v_pk_add_f32 v[0:1], v[0:1], 1.0 op_sel_hi:[1,0]
	s_nop 0
	v_div_scale_f32 v20, s[20:21], v1, v1, v18
	v_rcp_f32_e32 v21, v20
	s_nop 0
	v_fma_f32 v22, -v20, v21, 1.0
	v_fmac_f32_e32 v21, v22, v21
	v_div_scale_f32 v22, vcc, v18, v1, v18
	v_mul_f32_e32 v23, v22, v21
	v_fma_f32 v24, -v20, v23, v22
	v_fmac_f32_e32 v23, v24, v21
	v_fma_f32 v20, -v20, v23, v22
	v_div_fmas_f32 v20, v20, v21, v23
	v_div_fixup_f32 v1, v20, v1, v18
	v_div_scale_f32 v18, s[20:21], v0, v0, v19
	v_rcp_f32_e32 v20, v18
	s_nop 0
	v_fma_f32 v21, -v18, v20, 1.0
	v_fmac_f32_e32 v20, v21, v20
	v_div_scale_f32 v21, vcc, v19, v0, v19
	v_mul_f32_e32 v22, v21, v20
	v_fma_f32 v23, -v18, v22, v21
	v_fmac_f32_e32 v22, v23, v20
	v_fma_f32 v18, -v18, v22, v21
	v_div_fmas_f32 v18, v18, v20, v22
	v_div_fixup_f32 v0, v18, v0, v19
	v_and_b32_e32 v18, 0xffff0000, v124
	v_lshlrev_b32_e32 v2, 16, v124
	v_pk_mul_f32 v[0:1], v[14:15], v[0:1]
	v_mul_f32_e32 v14, 0xbfb8aa3b, v2
	v_mul_f32_e32 v8, 0xbfb8aa3b, v18
	v_exp_f32_e32 v14, v14
	v_exp_f32_e32 v15, v8
	s_nop 0
	v_pk_add_f32 v[8:9], v[14:15], 1.0 op_sel_hi:[1,0]
	s_nop 0
	v_div_scale_f32 v14, s[20:21], v9, v9, v18
	v_rcp_f32_e32 v15, v14
	s_nop 0
	v_fma_f32 v19, -v14, v15, 1.0
	v_fmac_f32_e32 v15, v19, v15
	v_div_scale_f32 v19, vcc, v18, v9, v18
	v_mul_f32_e32 v20, v19, v15
	v_fma_f32 v21, -v14, v20, v19
	v_fmac_f32_e32 v20, v21, v15
	v_fma_f32 v14, -v14, v20, v19
	v_div_fmas_f32 v14, v14, v15, v20
	v_div_fixup_f32 v9, v14, v9, v18
	v_div_scale_f32 v14, s[20:21], v8, v8, v2
	v_rcp_f32_e32 v15, v14
	s_nop 0
	v_fma_f32 v18, -v14, v15, 1.0
	v_fmac_f32_e32 v15, v18, v15
	v_div_scale_f32 v18, vcc, v2, v8, v2
	v_mul_f32_e32 v19, v18, v15
	v_fma_f32 v20, -v14, v19, v18
	v_fmac_f32_e32 v19, v20, v15
	v_fma_f32 v14, -v14, v19, v18
	v_div_fmas_f32 v14, v14, v15, v19
	v_div_fixup_f32 v8, v14, v8, v2
	v_pk_mul_f32 v[4:5], v[8:9], v[4:5]
	v_and_b32_e32 v8, 0xffff0000, v125
	v_lshlrev_b32_e32 v9, 16, v125
	v_mul_f32_e32 v2, 0xbfb8aa3b, v9
	v_mul_f32_e32 v3, 0xbfb8aa3b, v8
	v_exp_f32_e32 v2, v2
	v_exp_f32_e32 v3, v3
	s_nop 0
	v_pk_add_f32 v[2:3], v[2:3], 1.0 op_sel_hi:[1,0]
	s_nop 0
	v_div_scale_f32 v10, s[20:21], v3, v3, v8
	v_rcp_f32_e32 v11, v10
	s_nop 0
	v_fma_f32 v14, -v10, v11, 1.0
	v_fmac_f32_e32 v11, v14, v11
	v_div_scale_f32 v14, vcc, v8, v3, v8
	v_mul_f32_e32 v15, v14, v11
	v_fma_f32 v18, -v10, v15, v14
	v_fmac_f32_e32 v15, v18, v11
	v_fma_f32 v10, -v10, v15, v14
	v_div_fmas_f32 v10, v10, v11, v15
	v_div_fixup_f32 v3, v10, v3, v8
	v_div_scale_f32 v8, s[20:21], v2, v2, v9
	v_rcp_f32_e32 v10, v8
	s_nop 0
	v_fma_f32 v11, -v8, v10, 1.0
	v_fmac_f32_e32 v10, v11, v10
	v_div_scale_f32 v11, vcc, v9, v2, v9
	v_mul_f32_e32 v14, v11, v10
	v_fma_f32 v15, -v8, v14, v11
	v_fmac_f32_e32 v14, v15, v10
	v_fma_f32 v8, -v8, v14, v11
	v_div_fmas_f32 v8, v8, v10, v14
	v_div_fixup_f32 v2, v8, v2, v9
	v_pk_mul_f32 v[2:3], v[2:3], v[6:7]
	v_cvt_pk_bf16_f32 v4, v4, v5
	v_cvt_pk_bf16_f32 v2, v2, v3
	v_mov_b32_e32 v3, v2
	v_mov_b32_e32 v2, v4
	v_lshlrev_b64 v[4:5], 12, v[16:17]
	v_lshl_add_u64 v[4:5], s[30:31], 0, v[4:5]
	v_lshl_add_u64 v[4:5], v[4:5], 0, s[70:71]
	v_lshl_add_u64 v[4:5], v[4:5], 0, v[160:161]
	v_cvt_pk_bf16_f32 v12, v12, v13
	v_cvt_pk_bf16_f32 v0, v0, v1
	v_add_co_u32_e32 v4, vcc, 0xcc00000, v4
	v_mov_b32_e32 v1, v0
	v_mov_b32_e32 v0, v12
	v_addc_co_u32_e32 v5, vcc, 0, v5, vcc
	global_store_dwordx4 v[4:5], v[0:3], off offset:2048
	s_barrier
